# loop-back barrier moved below the K-loop counter SALU ops (back-edge rotation) on top of prologue de-serialisation
# baseline (speedup 1.0000x reference)
.LBB0_212:
	s_add_i32 s76, s38, 2
	s_add_u32 s39, s36, 0x80
	s_addc_u32 s77, s37, 0
	s_cmp_lg_u32 s75, s38
	s_cselect_b32 s78, s39, 0
	s_cselect_b32 s77, s77, 0
	s_add_u32 s38, s22, s78
	s_addc_u32 s39, s23, s77
	s_add_i32 s80, 0, 0x10000
	s_add_u32 s78, s34, s78
	v_add_u32_e32 v145, s80, v143
	s_addc_u32 s79, s35, s77
	s_add_i32 s77, 0, 0x14000
	ds_read_b128 v[146:149], v145
	ds_read_b128 v[150:153], v145 offset:1024
	ds_read_b128 v[154:157], v145 offset:2048
	ds_read_b128 v[158:161], v145 offset:3072
	v_add_u32_e32 v145, s77, v143
	ds_read_b128 v[162:165], v145
	ds_read_b128 v[166:169], v145 offset:1024
	ds_read_b128 v[170:173], v145 offset:2048
	ds_read_b128 v[174:177], v145 offset:3072
	v_lshl_add_u64 v[212:213], v[136:137], 0, s[36:37]
	s_add_i32 m0, s58, 0xc000
	ds_read_b128 v[180:183], v144
	ds_read_b128 v[184:187], v144 offset:1024
	ds_read_b128 v[188:191], v144 offset:2048
	ds_read_b128 v[192:195], v144 offset:3072
	ds_read_b128 v[196:199], v144 offset:4096
	ds_read_b128 v[200:203], v144 offset:5120
	ds_read_b128 v[204:207], v144 offset:6144
	ds_read_b128 v[208:211], v144 offset:7168
	global_load_lds_dwordx4 v[212:213], off
	v_lshl_add_u64 v[212:213], v[138:139], 0, s[36:37]
	s_add_i32 m0, s58, 0xe000
	s_nop 0
	global_load_lds_dwordx4 v[212:213], off
	s_waitcnt vmcnt(8)
	s_waitcnt lgkmcnt(0)
	s_barrier
	s_setprio 1
	s_waitcnt lgkmcnt(0)
	v_mfma_f32_16x16x32_bf16 v[124:127], v[146:149], v[180:183], v[124:127]
	v_mfma_f32_16x16x32_bf16 v[120:123], v[154:157], v[180:183], v[120:123]
	v_mfma_f32_16x16x32_bf16 v[116:119], v[146:149], v[188:191], v[116:119]
	v_mfma_f32_16x16x32_bf16 v[108:111], v[154:157], v[188:191], v[108:111]
	v_mfma_f32_16x16x32_bf16 v[100:103], v[146:149], v[196:199], v[100:103]
	v_mfma_f32_16x16x32_bf16 v[92:95], v[154:157], v[196:199], v[92:95]
	v_mfma_f32_16x16x32_bf16 v[84:87], v[146:149], v[204:207], v[84:87]
	v_mfma_f32_16x16x32_bf16 v[76:79], v[154:157], v[204:207], v[76:79]
	v_mfma_f32_16x16x32_bf16 v[124:127], v[150:153], v[184:187], v[124:127]
	v_mfma_f32_16x16x32_bf16 v[120:123], v[158:161], v[184:187], v[120:123]
	v_mfma_f32_16x16x32_bf16 v[116:119], v[150:153], v[192:195], v[116:119]
	v_mfma_f32_16x16x32_bf16 v[108:111], v[158:161], v[192:195], v[108:111]
	v_mfma_f32_16x16x32_bf16 v[100:103], v[150:153], v[200:203], v[100:103]
	v_mfma_f32_16x16x32_bf16 v[92:95], v[158:161], v[200:203], v[92:95]
	v_mfma_f32_16x16x32_bf16 v[84:87], v[150:153], v[208:211], v[84:87]
	v_mfma_f32_16x16x32_bf16 v[76:79], v[158:161], v[208:211], v[76:79]
	s_setprio 0
	s_setprio 1
	v_mfma_f32_16x16x32_bf16 v[112:115], v[162:165], v[180:183], v[112:115]
	v_mfma_f32_16x16x32_bf16 v[104:107], v[170:173], v[180:183], v[104:107]
	v_mfma_f32_16x16x32_bf16 v[96:99], v[162:165], v[188:191], v[96:99]
	v_mfma_f32_16x16x32_bf16 v[88:91], v[170:173], v[188:191], v[88:91]
	v_mfma_f32_16x16x32_bf16 v[80:83], v[162:165], v[196:199], v[80:83]
	v_mfma_f32_16x16x32_bf16 v[72:75], v[170:173], v[196:199], v[72:75]
	v_mfma_f32_16x16x32_bf16 v[68:71], v[162:165], v[204:207], v[68:71]
	v_mfma_f32_16x16x32_bf16 v[64:67], v[170:173], v[204:207], v[64:67]
	v_mfma_f32_16x16x32_bf16 v[112:115], v[166:169], v[184:187], v[112:115]
	v_mfma_f32_16x16x32_bf16 v[104:107], v[174:177], v[184:187], v[104:107]
	v_mfma_f32_16x16x32_bf16 v[96:99], v[166:169], v[192:195], v[96:99]
	v_mfma_f32_16x16x32_bf16 v[88:91], v[174:177], v[192:195], v[88:91]
	v_mfma_f32_16x16x32_bf16 v[80:83], v[166:169], v[200:203], v[80:83]
	v_mfma_f32_16x16x32_bf16 v[72:75], v[174:177], v[200:203], v[72:75]
	v_mfma_f32_16x16x32_bf16 v[68:71], v[166:169], v[208:211], v[68:71]
	v_mfma_f32_16x16x32_bf16 v[64:67], v[174:177], v[208:211], v[64:67]
	s_setprio 0
	s_barrier
	s_add_i32 s80, s80, s56
	v_lshl_add_u64 v[212:213], s[78:79], 0, v[128:129]
	s_mov_b32 m0, s80
	ds_read_b128 v[180:183], v144 offset:16384
	ds_read_b128 v[184:187], v144 offset:17408
	ds_read_b128 v[188:191], v144 offset:18432
	ds_read_b128 v[192:195], v144 offset:19456
	ds_read_b128 v[196:199], v144 offset:20480
	ds_read_b128 v[200:203], v144 offset:21504
	ds_read_b128 v[204:207], v144 offset:22528
	ds_read_b128 v[208:211], v144 offset:23552
	global_load_lds_dwordx4 v[212:213], off
	s_add_i32 m0, s80, 0x2000
	v_lshl_add_u64 v[214:215], s[78:79], 0, v[134:135]
	s_add_u32 s78, s78, s54
	s_addc_u32 s79, s79, 0
	s_add_i32 s77, s77, s56
	global_load_lds_dwordx4 v[214:215], off
	v_lshl_add_u64 v[216:217], s[78:79], 0, v[128:129]
	s_mov_b32 m0, s77
	v_lshl_add_u64 v[218:219], s[78:79], 0, v[134:135]
	global_load_lds_dwordx4 v[216:217], off
	s_add_i32 m0, s77, 0x2000
	v_lshl_add_u64 v[220:221], s[38:39], 0, v[130:131]
	global_load_lds_dwordx4 v[218:219], off
	s_mov_b32 m0, s58
	v_lshl_add_u64 v[222:223], s[38:39], 0, v[132:133]
	global_load_lds_dwordx4 v[220:221], off
	s_mov_b32 m0, s59
	s_nop 0
	global_load_lds_dwordx4 v[222:223], off
	s_waitcnt vmcnt(8)
	s_waitcnt lgkmcnt(0)
	s_barrier
	s_setprio 1
	s_waitcnt lgkmcnt(0)
	v_mfma_f32_16x16x32_bf16 v[60:63], v[146:149], v[180:183], v[60:63]
	v_mfma_f32_16x16x32_bf16 v[56:59], v[154:157], v[180:183], v[56:59]
	v_mfma_f32_16x16x32_bf16 v[52:55], v[146:149], v[188:191], v[52:55]
	v_mfma_f32_16x16x32_bf16 v[48:51], v[154:157], v[188:191], v[48:51]
	v_mfma_f32_16x16x32_bf16 v[36:39], v[146:149], v[196:199], v[36:39]
	v_mfma_f32_16x16x32_bf16 v[32:35], v[154:157], v[196:199], v[32:35]
	v_mfma_f32_16x16x32_bf16 v[20:23], v[146:149], v[204:207], v[20:23]
	v_mfma_f32_16x16x32_bf16 v[16:19], v[154:157], v[204:207], v[16:19]
	v_mfma_f32_16x16x32_bf16 v[60:63], v[150:153], v[184:187], v[60:63]
	v_mfma_f32_16x16x32_bf16 v[56:59], v[158:161], v[184:187], v[56:59]
	v_mfma_f32_16x16x32_bf16 v[52:55], v[150:153], v[192:195], v[52:55]
	v_mfma_f32_16x16x32_bf16 v[48:51], v[158:161], v[192:195], v[48:51]
	v_mfma_f32_16x16x32_bf16 v[36:39], v[150:153], v[200:203], v[36:39]
	v_mfma_f32_16x16x32_bf16 v[32:35], v[158:161], v[200:203], v[32:35]
	v_mfma_f32_16x16x32_bf16 v[20:23], v[150:153], v[208:211], v[20:23]
	v_mfma_f32_16x16x32_bf16 v[16:19], v[158:161], v[208:211], v[16:19]
	s_setprio 0
	s_setprio 1
	v_mfma_f32_16x16x32_bf16 v[44:47], v[162:165], v[180:183], v[44:47]
	v_mfma_f32_16x16x32_bf16 v[40:43], v[170:173], v[180:183], v[40:43]
	v_mfma_f32_16x16x32_bf16 v[28:31], v[162:165], v[188:191], v[28:31]
	v_mfma_f32_16x16x32_bf16 v[24:27], v[170:173], v[188:191], v[24:27]
	v_mfma_f32_16x16x32_bf16 v[12:15], v[162:165], v[196:199], v[12:15]
	v_mfma_f32_16x16x32_bf16 v[8:11], v[170:173], v[196:199], v[8:11]
	v_mfma_f32_16x16x32_bf16 v[4:7], v[162:165], v[204:207], v[4:7]
	v_mfma_f32_16x16x32_bf16 v[0:3], v[170:173], v[204:207], v[0:3]
	v_mfma_f32_16x16x32_bf16 v[44:47], v[166:169], v[184:187], v[44:47]
	v_mfma_f32_16x16x32_bf16 v[40:43], v[174:177], v[184:187], v[40:43]
	v_mfma_f32_16x16x32_bf16 v[28:31], v[166:169], v[192:195], v[28:31]
	v_mfma_f32_16x16x32_bf16 v[24:27], v[174:177], v[192:195], v[24:27]
	v_mfma_f32_16x16x32_bf16 v[12:15], v[166:169], v[200:203], v[12:15]
	v_mfma_f32_16x16x32_bf16 v[8:11], v[174:177], v[200:203], v[8:11]
	v_mfma_f32_16x16x32_bf16 v[4:7], v[166:169], v[208:211], v[4:7]
	v_mfma_f32_16x16x32_bf16 v[0:3], v[174:177], v[208:211], v[0:3]
	s_setprio 0
	s_barrier
	s_add_i32 s77, 0, 0x18000
	v_add_u32_e32 v145, s77, v143
	s_add_i32 s78, 0, 0x1c000
	ds_read_b128 v[146:149], v145
	ds_read_b128 v[150:153], v145 offset:1024
	ds_read_b128 v[154:157], v145 offset:2048
	ds_read_b128 v[158:161], v145 offset:3072
	v_add_u32_e32 v145, s78, v143
	ds_read_b128 v[162:165], v145
	ds_read_b128 v[166:169], v145 offset:1024
	ds_read_b128 v[170:173], v145 offset:2048
	ds_read_b128 v[174:177], v145 offset:3072
	s_add_u32 s38, s38, s24
	s_addc_u32 s39, s39, s25
	s_mov_b32 m0, s68
	v_lshl_add_u64 v[224:225], s[38:39], 0, v[130:131]
	ds_read_b128 v[180:183], v144 offset:32768
	ds_read_b128 v[184:187], v144 offset:33792
	ds_read_b128 v[188:191], v144 offset:34816
	ds_read_b128 v[192:195], v144 offset:35840
	ds_read_b128 v[196:199], v144 offset:36864
	ds_read_b128 v[200:203], v144 offset:37888
	ds_read_b128 v[204:207], v144 offset:38912
	ds_read_b128 v[208:211], v144 offset:39936
	global_load_lds_dwordx4 v[224:225], off
	v_lshl_add_u64 v[224:225], s[38:39], 0, v[132:133]
	s_mov_b32 m0, s69
	s_nop 0
	global_load_lds_dwordx4 v[224:225], off
	s_waitcnt vmcnt(8)
	s_waitcnt lgkmcnt(0)
	s_barrier
	s_setprio 1
	s_waitcnt lgkmcnt(0)
	v_mfma_f32_16x16x32_bf16 v[124:127], v[146:149], v[180:183], v[124:127]
	v_mfma_f32_16x16x32_bf16 v[120:123], v[154:157], v[180:183], v[120:123]
	v_mfma_f32_16x16x32_bf16 v[116:119], v[146:149], v[188:191], v[116:119]
	v_mfma_f32_16x16x32_bf16 v[108:111], v[154:157], v[188:191], v[108:111]
	v_mfma_f32_16x16x32_bf16 v[100:103], v[146:149], v[196:199], v[100:103]
	v_mfma_f32_16x16x32_bf16 v[92:95], v[154:157], v[196:199], v[92:95]
	v_mfma_f32_16x16x32_bf16 v[84:87], v[146:149], v[204:207], v[84:87]
	v_mfma_f32_16x16x32_bf16 v[76:79], v[154:157], v[204:207], v[76:79]
	v_mfma_f32_16x16x32_bf16 v[124:127], v[150:153], v[184:187], v[124:127]
	v_mfma_f32_16x16x32_bf16 v[120:123], v[158:161], v[184:187], v[120:123]
	v_mfma_f32_16x16x32_bf16 v[116:119], v[150:153], v[192:195], v[116:119]
	v_mfma_f32_16x16x32_bf16 v[108:111], v[158:161], v[192:195], v[108:111]
	v_mfma_f32_16x16x32_bf16 v[100:103], v[150:153], v[200:203], v[100:103]
	v_mfma_f32_16x16x32_bf16 v[92:95], v[158:161], v[200:203], v[92:95]
	v_mfma_f32_16x16x32_bf16 v[84:87], v[150:153], v[208:211], v[84:87]
	v_mfma_f32_16x16x32_bf16 v[76:79], v[158:161], v[208:211], v[76:79]
	s_setprio 0
	s_setprio 1
	v_mfma_f32_16x16x32_bf16 v[112:115], v[162:165], v[180:183], v[112:115]
	v_mfma_f32_16x16x32_bf16 v[104:107], v[170:173], v[180:183], v[104:107]
	v_mfma_f32_16x16x32_bf16 v[96:99], v[162:165], v[188:191], v[96:99]
	v_mfma_f32_16x16x32_bf16 v[88:91], v[170:173], v[188:191], v[88:91]
	v_mfma_f32_16x16x32_bf16 v[80:83], v[162:165], v[196:199], v[80:83]
	v_mfma_f32_16x16x32_bf16 v[72:75], v[170:173], v[196:199], v[72:75]
	v_mfma_f32_16x16x32_bf16 v[68:71], v[162:165], v[204:207], v[68:71]
	v_mfma_f32_16x16x32_bf16 v[64:67], v[170:173], v[204:207], v[64:67]
	v_mfma_f32_16x16x32_bf16 v[112:115], v[166:169], v[184:187], v[112:115]
	v_mfma_f32_16x16x32_bf16 v[104:107], v[174:177], v[184:187], v[104:107]
	v_mfma_f32_16x16x32_bf16 v[96:99], v[166:169], v[192:195], v[96:99]
	v_mfma_f32_16x16x32_bf16 v[88:91], v[174:177], v[192:195], v[88:91]
	v_mfma_f32_16x16x32_bf16 v[80:83], v[166:169], v[200:203], v[80:83]
	v_mfma_f32_16x16x32_bf16 v[72:75], v[174:177], v[200:203], v[72:75]
	v_mfma_f32_16x16x32_bf16 v[68:71], v[166:169], v[208:211], v[68:71]
	v_mfma_f32_16x16x32_bf16 v[64:67], v[174:177], v[208:211], v[64:67]
	s_setprio 0
	s_barrier
	s_add_i32 s38, s77, s56
	v_lshl_add_u64 v[212:213], v[212:213], 0, s[14:15]
	s_mov_b32 m0, s38
	ds_read_b128 v[180:183], v144 offset:49152
	ds_read_b128 v[184:187], v144 offset:50176
	ds_read_b128 v[188:191], v144 offset:51200
	ds_read_b128 v[192:195], v144 offset:52224
	ds_read_b128 v[196:199], v144 offset:53248
	ds_read_b128 v[200:203], v144 offset:54272
	ds_read_b128 v[204:207], v144 offset:55296
	ds_read_b128 v[208:211], v144 offset:56320
	global_load_lds_dwordx4 v[212:213], off
	v_lshl_add_u64 v[212:213], v[214:215], 0, s[14:15]
	s_add_i32 m0, s38, 0x2000
	s_add_i32 s38, s78, s56
	global_load_lds_dwordx4 v[212:213], off
	v_lshl_add_u64 v[212:213], v[216:217], 0, s[14:15]
	s_mov_b32 m0, s38
	s_nop 0
	global_load_lds_dwordx4 v[212:213], off
	v_lshl_add_u64 v[212:213], v[218:219], 0, s[14:15]
	s_add_i32 m0, s38, 0x2000
	s_nop 0
	global_load_lds_dwordx4 v[212:213], off
	v_lshl_add_u64 v[212:213], v[220:221], 0, s[14:15]
	s_mov_b32 m0, s73
	s_nop 0
	global_load_lds_dwordx4 v[212:213], off
	v_lshl_add_u64 v[212:213], v[222:223], 0, s[14:15]
	s_mov_b32 m0, s74
	s_nop 0
	global_load_lds_dwordx4 v[212:213], off
	s_waitcnt vmcnt(8)
	s_waitcnt lgkmcnt(0)
	s_barrier
	s_setprio 1
	s_waitcnt lgkmcnt(0)
	v_mfma_f32_16x16x32_bf16 v[60:63], v[146:149], v[180:183], v[60:63]
	v_mfma_f32_16x16x32_bf16 v[56:59], v[154:157], v[180:183], v[56:59]
	v_mfma_f32_16x16x32_bf16 v[52:55], v[146:149], v[188:191], v[52:55]
	v_mfma_f32_16x16x32_bf16 v[48:51], v[154:157], v[188:191], v[48:51]
	v_mfma_f32_16x16x32_bf16 v[36:39], v[146:149], v[196:199], v[36:39]
	v_mfma_f32_16x16x32_bf16 v[32:35], v[154:157], v[196:199], v[32:35]
	v_mfma_f32_16x16x32_bf16 v[20:23], v[146:149], v[204:207], v[20:23]
	v_mfma_f32_16x16x32_bf16 v[16:19], v[154:157], v[204:207], v[16:19]
	v_mfma_f32_16x16x32_bf16 v[60:63], v[150:153], v[184:187], v[60:63]
	v_mfma_f32_16x16x32_bf16 v[56:59], v[158:161], v[184:187], v[56:59]
	v_mfma_f32_16x16x32_bf16 v[52:55], v[150:153], v[192:195], v[52:55]
	v_mfma_f32_16x16x32_bf16 v[48:51], v[158:161], v[192:195], v[48:51]
	v_mfma_f32_16x16x32_bf16 v[36:39], v[150:153], v[200:203], v[36:39]
	v_mfma_f32_16x16x32_bf16 v[32:35], v[158:161], v[200:203], v[32:35]
	v_mfma_f32_16x16x32_bf16 v[20:23], v[150:153], v[208:211], v[20:23]
	v_mfma_f32_16x16x32_bf16 v[16:19], v[158:161], v[208:211], v[16:19]
	s_setprio 0
	s_setprio 1
	v_mfma_f32_16x16x32_bf16 v[44:47], v[162:165], v[180:183], v[44:47]
	v_mfma_f32_16x16x32_bf16 v[40:43], v[170:173], v[180:183], v[40:43]
	v_mfma_f32_16x16x32_bf16 v[28:31], v[162:165], v[188:191], v[28:31]
	v_mfma_f32_16x16x32_bf16 v[24:27], v[170:173], v[188:191], v[24:27]
	v_mfma_f32_16x16x32_bf16 v[12:15], v[162:165], v[196:199], v[12:15]
	v_mfma_f32_16x16x32_bf16 v[8:11], v[170:173], v[196:199], v[8:11]
	v_mfma_f32_16x16x32_bf16 v[4:7], v[162:165], v[204:207], v[4:7]
	v_mfma_f32_16x16x32_bf16 v[0:3], v[170:173], v[204:207], v[0:3]
	v_mfma_f32_16x16x32_bf16 v[44:47], v[166:169], v[184:187], v[44:47]
	v_mfma_f32_16x16x32_bf16 v[40:43], v[174:177], v[184:187], v[40:43]
	v_mfma_f32_16x16x32_bf16 v[28:31], v[166:169], v[192:195], v[28:31]
	v_mfma_f32_16x16x32_bf16 v[24:27], v[174:177], v[192:195], v[24:27]
	v_mfma_f32_16x16x32_bf16 v[12:15], v[166:169], v[200:203], v[12:15]
	v_mfma_f32_16x16x32_bf16 v[8:11], v[174:177], v[200:203], v[8:11]
	v_mfma_f32_16x16x32_bf16 v[4:7], v[166:169], v[208:211], v[4:7]
	v_mfma_f32_16x16x32_bf16 v[0:3], v[174:177], v[208:211], v[0:3]
	s_setprio 0
	s_add_u32 s36, s36, 0x100
	s_addc_u32 s37, s37, 0
	s_cmp_ge_u32 s76, s72
	s_mov_b32 s38, s76
	s_barrier
	s_cbranch_scc0 .LBB0_212
	s_cmpk_lt_u32 s4, 0x100
	s_cbranch_scc0 .LBB0_199
	s_barrier
	s_branch .LBB0_199

.LBB0_359:
	s_add_u32 s18, s44, 0xfff80080
	s_addc_u32 s19, s45, -1
	s_add_i32 s67, 0, 0x10000
	s_cmp_eq_u32 s41, 28
	s_cselect_b32 s49, s39, s19
	s_cselect_b32 s48, s38, s18
	s_cselect_b32 s47, s43, s22
	s_cselect_b32 s46, s42, s21
	s_add_i32 s18, 0, 0x14000
	v_add_u32_e32 v142, s67, v160
	v_add_u32_e32 v156, s18, v160
	ds_read_b128 v[130:133], v142
	ds_read_b128 v[134:137], v142 offset:1024
	ds_read_b128 v[138:141], v142 offset:2048
	ds_read_b128 v[142:145], v142 offset:3072
	ds_read_b128 v[162:165], v156
	ds_read_b128 v[166:169], v156 offset:1024
	ds_read_b128 v[170:173], v156 offset:2048
	ds_read_b128 v[174:177], v156 offset:3072
	v_lshl_add_u64 v[156:157], s[44:45], 0, v[152:153]
	s_add_i32 m0, s30, 0xc000
	ds_read_b128 v[184:187], v161
	ds_read_b128 v[188:191], v161 offset:1024
	ds_read_b128 v[192:195], v161 offset:2048
	ds_read_b128 v[196:199], v161 offset:3072
	ds_read_b128 v[200:203], v161 offset:4096
	ds_read_b128 v[204:207], v161 offset:5120
	ds_read_b128 v[208:211], v161 offset:6144
	ds_read_b128 v[212:215], v161 offset:7168
	global_load_lds_dwordx4 v[156:157], off
	v_lshl_add_u64 v[156:157], s[44:45], 0, v[154:155]
	s_add_i32 m0, s30, 0xe000
	s_nop 0
	global_load_lds_dwordx4 v[156:157], off
	s_waitcnt vmcnt(8)
	s_waitcnt lgkmcnt(0)
	s_barrier
	s_setprio 1
	s_waitcnt lgkmcnt(0)
	v_mfma_f32_16x16x32_bf16 v[126:129], v[130:133], v[184:187], v[126:129]
	v_mfma_f32_16x16x32_bf16 v[122:125], v[138:141], v[184:187], v[122:125]
	v_mfma_f32_16x16x32_bf16 v[110:113], v[130:133], v[192:195], v[110:113]
	v_mfma_f32_16x16x32_bf16 v[106:109], v[138:141], v[192:195], v[106:109]
	v_mfma_f32_16x16x32_bf16 v[94:97], v[130:133], v[200:203], v[94:97]
	v_mfma_f32_16x16x32_bf16 v[90:93], v[138:141], v[200:203], v[90:93]
	v_mfma_f32_16x16x32_bf16 v[78:81], v[130:133], v[208:211], v[78:81]
	v_mfma_f32_16x16x32_bf16 v[74:77], v[138:141], v[208:211], v[74:77]
	v_mfma_f32_16x16x32_bf16 v[126:129], v[134:137], v[188:191], v[126:129]
	v_mfma_f32_16x16x32_bf16 v[122:125], v[142:145], v[188:191], v[122:125]
	v_mfma_f32_16x16x32_bf16 v[110:113], v[134:137], v[196:199], v[110:113]
	v_mfma_f32_16x16x32_bf16 v[106:109], v[142:145], v[196:199], v[106:109]
	v_mfma_f32_16x16x32_bf16 v[94:97], v[134:137], v[204:207], v[94:97]
	v_mfma_f32_16x16x32_bf16 v[90:93], v[142:145], v[204:207], v[90:93]
	v_mfma_f32_16x16x32_bf16 v[78:81], v[134:137], v[212:215], v[78:81]
	v_mfma_f32_16x16x32_bf16 v[74:77], v[142:145], v[212:215], v[74:77]
	s_setprio 0
	s_setprio 1
	v_mfma_f32_16x16x32_bf16 v[118:121], v[162:165], v[184:187], v[118:121]
	v_mfma_f32_16x16x32_bf16 v[114:117], v[170:173], v[184:187], v[114:117]
	v_mfma_f32_16x16x32_bf16 v[102:105], v[162:165], v[192:195], v[102:105]
	v_mfma_f32_16x16x32_bf16 v[98:101], v[170:173], v[192:195], v[98:101]
	v_mfma_f32_16x16x32_bf16 v[86:89], v[162:165], v[200:203], v[86:89]
	v_mfma_f32_16x16x32_bf16 v[82:85], v[170:173], v[200:203], v[82:85]
	v_mfma_f32_16x16x32_bf16 v[70:73], v[162:165], v[208:211], v[70:73]
	v_mfma_f32_16x16x32_bf16 v[66:69], v[170:173], v[208:211], v[66:69]
	v_mfma_f32_16x16x32_bf16 v[118:121], v[166:169], v[188:191], v[118:121]
	v_mfma_f32_16x16x32_bf16 v[114:117], v[174:177], v[188:191], v[114:117]
	v_mfma_f32_16x16x32_bf16 v[102:105], v[166:169], v[196:199], v[102:105]
	v_mfma_f32_16x16x32_bf16 v[98:101], v[174:177], v[196:199], v[98:101]
	v_mfma_f32_16x16x32_bf16 v[86:89], v[166:169], v[204:207], v[86:89]
	v_mfma_f32_16x16x32_bf16 v[82:85], v[174:177], v[204:207], v[82:85]
	v_mfma_f32_16x16x32_bf16 v[70:73], v[166:169], v[212:215], v[70:73]
	v_mfma_f32_16x16x32_bf16 v[66:69], v[174:177], v[212:215], v[66:69]
	s_setprio 0
	s_barrier
	s_add_i32 s19, s67, s5
	v_lshl_add_u64 v[156:157], s[46:47], 0, v[0:1]
	s_mov_b32 m0, s19
	ds_read_b128 v[184:187], v161 offset:16384
	ds_read_b128 v[188:191], v161 offset:17408
	ds_read_b128 v[192:195], v161 offset:18432
	ds_read_b128 v[196:199], v161 offset:19456
	ds_read_b128 v[200:203], v161 offset:20480
	ds_read_b128 v[204:207], v161 offset:21504
	ds_read_b128 v[208:211], v161 offset:22528
	ds_read_b128 v[212:215], v161 offset:23552
	global_load_lds_dwordx4 v[156:157], off
	s_add_i32 m0, s19, 0x2000
	s_add_u32 s74, s46, 0x80000
	v_lshl_add_u64 v[216:217], s[46:47], 0, v[146:147]
	s_addc_u32 s75, s47, 0
	s_add_i32 s18, s18, s5
	global_load_lds_dwordx4 v[216:217], off
	v_lshl_add_u64 v[218:219], s[74:75], 0, v[0:1]
	s_mov_b32 m0, s18
	v_lshl_add_u64 v[220:221], s[48:49], 0, v[148:149]
	global_load_lds_dwordx4 v[218:219], off
	v_lshl_add_u64 v[218:219], s[74:75], 0, v[146:147]
	s_add_i32 m0, s18, 0x2000
	s_nop 0
	global_load_lds_dwordx4 v[218:219], off
	v_lshl_add_u64 v[218:219], s[48:49], 0, v[150:151]
	s_mov_b32 m0, s30
	s_nop 0
	global_load_lds_dwordx4 v[218:219], off
	s_mov_b32 m0, s33
	s_nop 0
	global_load_lds_dwordx4 v[220:221], off
	s_waitcnt vmcnt(8)
	s_waitcnt lgkmcnt(0)
	s_barrier
	s_setprio 1
	s_waitcnt lgkmcnt(0)
	v_mfma_f32_16x16x32_bf16 v[62:65], v[130:133], v[184:187], v[62:65]
	v_mfma_f32_16x16x32_bf16 v[58:61], v[138:141], v[184:187], v[58:61]
	v_mfma_f32_16x16x32_bf16 v[46:49], v[130:133], v[192:195], v[46:49]
	v_mfma_f32_16x16x32_bf16 v[42:45], v[138:141], v[192:195], v[42:45]
	v_mfma_f32_16x16x32_bf16 v[30:33], v[130:133], v[200:203], v[30:33]
	v_mfma_f32_16x16x32_bf16 v[26:29], v[138:141], v[200:203], v[26:29]
	v_mfma_f32_16x16x32_bf16 v[14:17], v[130:133], v[208:211], v[14:17]
	v_mfma_f32_16x16x32_bf16 v[10:13], v[138:141], v[208:211], v[10:13]
	v_mfma_f32_16x16x32_bf16 v[62:65], v[134:137], v[188:191], v[62:65]
	v_mfma_f32_16x16x32_bf16 v[58:61], v[142:145], v[188:191], v[58:61]
	v_mfma_f32_16x16x32_bf16 v[46:49], v[134:137], v[196:199], v[46:49]
	v_mfma_f32_16x16x32_bf16 v[42:45], v[142:145], v[196:199], v[42:45]
	v_mfma_f32_16x16x32_bf16 v[30:33], v[134:137], v[204:207], v[30:33]
	v_mfma_f32_16x16x32_bf16 v[26:29], v[142:145], v[204:207], v[26:29]
	v_mfma_f32_16x16x32_bf16 v[14:17], v[134:137], v[212:215], v[14:17]
	v_mfma_f32_16x16x32_bf16 v[10:13], v[142:145], v[212:215], v[10:13]
	s_setprio 0
	s_setprio 1
	v_mfma_f32_16x16x32_bf16 v[54:57], v[162:165], v[184:187], v[54:57]
	v_mfma_f32_16x16x32_bf16 v[50:53], v[170:173], v[184:187], v[50:53]
	v_mfma_f32_16x16x32_bf16 v[38:41], v[162:165], v[192:195], v[38:41]
	v_mfma_f32_16x16x32_bf16 v[34:37], v[170:173], v[192:195], v[34:37]
	v_mfma_f32_16x16x32_bf16 v[22:25], v[162:165], v[200:203], v[22:25]
	v_mfma_f32_16x16x32_bf16 v[18:21], v[170:173], v[200:203], v[18:21]
	v_mfma_f32_16x16x32_bf16 v[6:9], v[162:165], v[208:211], v[6:9]
	v_mfma_f32_16x16x32_bf16 v[2:5], v[170:173], v[208:211], v[2:5]
	v_mfma_f32_16x16x32_bf16 v[54:57], v[166:169], v[188:191], v[54:57]
	v_mfma_f32_16x16x32_bf16 v[50:53], v[174:177], v[188:191], v[50:53]
	v_mfma_f32_16x16x32_bf16 v[38:41], v[166:169], v[196:199], v[38:41]
	v_mfma_f32_16x16x32_bf16 v[34:37], v[174:177], v[196:199], v[34:37]
	v_mfma_f32_16x16x32_bf16 v[22:25], v[166:169], v[204:207], v[22:25]
	v_mfma_f32_16x16x32_bf16 v[18:21], v[174:177], v[204:207], v[18:21]
	v_mfma_f32_16x16x32_bf16 v[6:9], v[166:169], v[212:215], v[6:9]
	v_mfma_f32_16x16x32_bf16 v[2:5], v[174:177], v[212:215], v[2:5]
	s_setprio 0
	s_barrier
	s_add_i32 s18, 0, 0x18000
	s_add_i32 s19, 0, 0x1c000
	v_add_u32_e32 v142, s18, v160
	v_add_u32_e32 v174, s19, v160
	ds_read_b128 v[130:133], v142
	ds_read_b128 v[134:137], v142 offset:1024
	ds_read_b128 v[138:141], v142 offset:2048
	ds_read_b128 v[142:145], v142 offset:3072
	ds_read_b128 v[162:165], v174
	ds_read_b128 v[166:169], v174 offset:1024
	ds_read_b128 v[170:173], v174 offset:2048
	ds_read_b128 v[174:177], v174 offset:3072
	s_add_u32 s48, s48, 0x80000
	s_addc_u32 s49, s49, 0
	s_mov_b32 m0, s36
	v_lshl_add_u64 v[222:223], s[48:49], 0, v[150:151]
	ds_read_b128 v[184:187], v161 offset:32768
	ds_read_b128 v[188:191], v161 offset:33792
	ds_read_b128 v[192:195], v161 offset:34816
	ds_read_b128 v[196:199], v161 offset:35840
	ds_read_b128 v[200:203], v161 offset:36864
	ds_read_b128 v[204:207], v161 offset:37888
	ds_read_b128 v[208:211], v161 offset:38912
	ds_read_b128 v[212:215], v161 offset:39936
	global_load_lds_dwordx4 v[222:223], off
	v_lshl_add_u64 v[222:223], s[48:49], 0, v[148:149]
	s_mov_b32 m0, s37
	s_nop 0
	global_load_lds_dwordx4 v[222:223], off
	s_waitcnt vmcnt(8)
	s_waitcnt lgkmcnt(0)
	s_barrier
	s_setprio 1
	s_waitcnt lgkmcnt(0)
	v_mfma_f32_16x16x32_bf16 v[126:129], v[130:133], v[184:187], v[126:129]
	v_mfma_f32_16x16x32_bf16 v[122:125], v[138:141], v[184:187], v[122:125]
	v_mfma_f32_16x16x32_bf16 v[110:113], v[130:133], v[192:195], v[110:113]
	v_mfma_f32_16x16x32_bf16 v[106:109], v[138:141], v[192:195], v[106:109]
	v_mfma_f32_16x16x32_bf16 v[94:97], v[130:133], v[200:203], v[94:97]
	v_mfma_f32_16x16x32_bf16 v[90:93], v[138:141], v[200:203], v[90:93]
	v_mfma_f32_16x16x32_bf16 v[78:81], v[130:133], v[208:211], v[78:81]
	v_mfma_f32_16x16x32_bf16 v[74:77], v[138:141], v[208:211], v[74:77]
	v_mfma_f32_16x16x32_bf16 v[126:129], v[134:137], v[188:191], v[126:129]
	v_mfma_f32_16x16x32_bf16 v[122:125], v[142:145], v[188:191], v[122:125]
	v_mfma_f32_16x16x32_bf16 v[110:113], v[134:137], v[196:199], v[110:113]
	v_mfma_f32_16x16x32_bf16 v[106:109], v[142:145], v[196:199], v[106:109]
	v_mfma_f32_16x16x32_bf16 v[94:97], v[134:137], v[204:207], v[94:97]
	v_mfma_f32_16x16x32_bf16 v[90:93], v[142:145], v[204:207], v[90:93]
	v_mfma_f32_16x16x32_bf16 v[78:81], v[134:137], v[212:215], v[78:81]
	v_mfma_f32_16x16x32_bf16 v[74:77], v[142:145], v[212:215], v[74:77]
	s_setprio 0
	s_setprio 1
	v_mfma_f32_16x16x32_bf16 v[118:121], v[162:165], v[184:187], v[118:121]
	v_mfma_f32_16x16x32_bf16 v[114:117], v[170:173], v[184:187], v[114:117]
	v_mfma_f32_16x16x32_bf16 v[102:105], v[162:165], v[192:195], v[102:105]
	v_mfma_f32_16x16x32_bf16 v[98:101], v[170:173], v[192:195], v[98:101]
	v_mfma_f32_16x16x32_bf16 v[86:89], v[162:165], v[200:203], v[86:89]
	v_mfma_f32_16x16x32_bf16 v[82:85], v[170:173], v[200:203], v[82:85]
	v_mfma_f32_16x16x32_bf16 v[70:73], v[162:165], v[208:211], v[70:73]
	v_mfma_f32_16x16x32_bf16 v[66:69], v[170:173], v[208:211], v[66:69]
	v_mfma_f32_16x16x32_bf16 v[118:121], v[166:169], v[188:191], v[118:121]
	v_mfma_f32_16x16x32_bf16 v[114:117], v[174:177], v[188:191], v[114:117]
	v_mfma_f32_16x16x32_bf16 v[102:105], v[166:169], v[196:199], v[102:105]
	v_mfma_f32_16x16x32_bf16 v[98:101], v[174:177], v[196:199], v[98:101]
	v_mfma_f32_16x16x32_bf16 v[86:89], v[166:169], v[204:207], v[86:89]
	v_mfma_f32_16x16x32_bf16 v[82:85], v[174:177], v[204:207], v[82:85]
	v_mfma_f32_16x16x32_bf16 v[70:73], v[166:169], v[212:215], v[70:73]
	v_mfma_f32_16x16x32_bf16 v[66:69], v[174:177], v[212:215], v[66:69]
	s_setprio 0
	s_barrier
	s_add_i32 s18, s18, s5
	v_lshl_add_u64 v[156:157], v[156:157], 0, s[90:91]
	s_mov_b32 m0, s18
	ds_read_b128 v[184:187], v161 offset:49152
	ds_read_b128 v[188:191], v161 offset:50176
	ds_read_b128 v[192:195], v161 offset:51200
	ds_read_b128 v[196:199], v161 offset:52224
	ds_read_b128 v[200:203], v161 offset:53248
	ds_read_b128 v[204:207], v161 offset:54272
	ds_read_b128 v[208:211], v161 offset:55296
	ds_read_b128 v[212:215], v161 offset:56320
	global_load_lds_dwordx4 v[156:157], off
	s_add_i32 m0, s18, 0x2000
	s_add_u32 s46, s46, 0x80080
	v_lshl_add_u64 v[156:157], v[216:217], 0, s[90:91]
	s_addc_u32 s47, s47, 0
	s_add_i32 s18, s19, s5
	global_load_lds_dwordx4 v[156:157], off
	v_lshl_add_u64 v[156:157], s[46:47], 0, v[0:1]
	s_mov_b32 m0, s18
	s_nop 0
	global_load_lds_dwordx4 v[156:157], off
	v_lshl_add_u64 v[156:157], s[46:47], 0, v[146:147]
	s_add_i32 m0, s18, 0x2000
	s_nop 0
	global_load_lds_dwordx4 v[156:157], off
	v_lshl_add_u64 v[156:157], v[218:219], 0, s[90:91]
	s_mov_b32 m0, s52
	s_nop 0
	global_load_lds_dwordx4 v[156:157], off
	v_lshl_add_u64 v[156:157], v[220:221], 0, s[90:91]
	s_mov_b32 m0, s53
	s_nop 0
	global_load_lds_dwordx4 v[156:157], off
	s_waitcnt vmcnt(8)
	s_waitcnt lgkmcnt(0)
	s_barrier
	s_setprio 1
	s_waitcnt lgkmcnt(0)
	v_mfma_f32_16x16x32_bf16 v[62:65], v[130:133], v[184:187], v[62:65]
	v_mfma_f32_16x16x32_bf16 v[58:61], v[138:141], v[184:187], v[58:61]
	v_mfma_f32_16x16x32_bf16 v[46:49], v[130:133], v[192:195], v[46:49]
	v_mfma_f32_16x16x32_bf16 v[42:45], v[138:141], v[192:195], v[42:45]
	v_mfma_f32_16x16x32_bf16 v[30:33], v[130:133], v[200:203], v[30:33]
	v_mfma_f32_16x16x32_bf16 v[26:29], v[138:141], v[200:203], v[26:29]
	v_mfma_f32_16x16x32_bf16 v[14:17], v[130:133], v[208:211], v[14:17]
	v_mfma_f32_16x16x32_bf16 v[10:13], v[138:141], v[208:211], v[10:13]
	v_mfma_f32_16x16x32_bf16 v[62:65], v[134:137], v[188:191], v[62:65]
	v_mfma_f32_16x16x32_bf16 v[58:61], v[142:145], v[188:191], v[58:61]
	v_mfma_f32_16x16x32_bf16 v[46:49], v[134:137], v[196:199], v[46:49]
	v_mfma_f32_16x16x32_bf16 v[42:45], v[142:145], v[196:199], v[42:45]
	v_mfma_f32_16x16x32_bf16 v[30:33], v[134:137], v[204:207], v[30:33]
	v_mfma_f32_16x16x32_bf16 v[26:29], v[142:145], v[204:207], v[26:29]
	v_mfma_f32_16x16x32_bf16 v[14:17], v[134:137], v[212:215], v[14:17]
	v_mfma_f32_16x16x32_bf16 v[10:13], v[142:145], v[212:215], v[10:13]
	s_setprio 0
	s_setprio 1
	v_mfma_f32_16x16x32_bf16 v[54:57], v[162:165], v[184:187], v[54:57]
	v_mfma_f32_16x16x32_bf16 v[50:53], v[170:173], v[184:187], v[50:53]
	v_mfma_f32_16x16x32_bf16 v[38:41], v[162:165], v[192:195], v[38:41]
	v_mfma_f32_16x16x32_bf16 v[34:37], v[170:173], v[192:195], v[34:37]
	v_mfma_f32_16x16x32_bf16 v[22:25], v[162:165], v[200:203], v[22:25]
	v_mfma_f32_16x16x32_bf16 v[18:21], v[170:173], v[200:203], v[18:21]
	v_mfma_f32_16x16x32_bf16 v[6:9], v[162:165], v[208:211], v[6:9]
	v_mfma_f32_16x16x32_bf16 v[2:5], v[170:173], v[208:211], v[2:5]
	v_mfma_f32_16x16x32_bf16 v[54:57], v[166:169], v[188:191], v[54:57]
	v_mfma_f32_16x16x32_bf16 v[50:53], v[174:177], v[188:191], v[50:53]
	v_mfma_f32_16x16x32_bf16 v[38:41], v[166:169], v[196:199], v[38:41]
	v_mfma_f32_16x16x32_bf16 v[34:37], v[174:177], v[196:199], v[34:37]
	v_mfma_f32_16x16x32_bf16 v[22:25], v[166:169], v[204:207], v[22:25]
	v_mfma_f32_16x16x32_bf16 v[18:21], v[174:177], v[204:207], v[18:21]
	v_mfma_f32_16x16x32_bf16 v[6:9], v[166:169], v[212:215], v[6:9]
	v_mfma_f32_16x16x32_bf16 v[2:5], v[174:177], v[212:215], v[2:5]
	s_setprio 0
	s_add_i32 s41, s41, 2
	s_add_u32 s44, s44, 0x100
	s_addc_u32 s45, s45, 0
	s_add_u32 s21, s21, 0x100
	s_addc_u32 s22, s22, 0
	s_cmp_gt_u32 s41, 29
	s_barrier
	s_cbranch_scc0 .LBB0_359
	s_and_b64 vcc, exec, s[10:11]
	s_cbranch_vccz .LBB0_362
	s_barrier

.LBB0_615:
	s_add_i32 s44, s16, 2
	s_add_u32 s17, s14, 0x80
	s_addc_u32 s18, s15, 0
	s_cmp_lg_u32 s43, s16
	s_cselect_b32 s19, s17, 0
	s_cselect_b32 s18, s18, 0
	s_add_u32 s16, s8, s19
	s_addc_u32 s17, s9, s18
	s_add_i32 s45, 0, 0x10000
	s_add_u32 s46, s12, s19
	s_addc_u32 s47, s13, s18
	s_add_i32 s18, 0, 0x14000
	v_add_u32_e32 v156, s45, v142
	v_add_u32_e32 v172, s18, v142
	ds_read_b128 v[144:147], v156
	ds_read_b128 v[148:151], v156 offset:1024
	ds_read_b128 v[152:155], v156 offset:2048
	ds_read_b128 v[156:159], v156 offset:3072
	ds_read_b128 v[160:163], v172
	ds_read_b128 v[164:167], v172 offset:1024
	ds_read_b128 v[168:171], v172 offset:2048
	ds_read_b128 v[172:175], v172 offset:3072
	v_lshl_add_u64 v[176:177], v[136:137], 0, s[14:15]
	s_add_i32 m0, s22, 0xc000
	ds_read_b128 v[184:187], v143
	ds_read_b128 v[188:191], v143 offset:1024
	ds_read_b128 v[192:195], v143 offset:2048
	ds_read_b128 v[196:199], v143 offset:3072
	ds_read_b128 v[200:203], v143 offset:4096
	ds_read_b128 v[204:207], v143 offset:5120
	ds_read_b128 v[208:211], v143 offset:6144
	ds_read_b128 v[212:215], v143 offset:7168
	global_load_lds_dwordx4 v[176:177], off
	v_lshl_add_u64 v[176:177], v[138:139], 0, s[14:15]
	s_add_i32 m0, s22, 0xe000
	s_nop 0
	global_load_lds_dwordx4 v[176:177], off
	s_waitcnt vmcnt(8)
	s_waitcnt lgkmcnt(0)
	s_barrier
	s_setprio 1
	s_waitcnt lgkmcnt(0)
	v_mfma_f32_16x16x32_bf16 v[126:129], v[144:147], v[184:187], v[126:129]
	v_mfma_f32_16x16x32_bf16 v[122:125], v[152:155], v[184:187], v[122:125]
	v_mfma_f32_16x16x32_bf16 v[118:121], v[144:147], v[192:195], v[118:121]
	v_mfma_f32_16x16x32_bf16 v[110:113], v[152:155], v[192:195], v[110:113]
	v_mfma_f32_16x16x32_bf16 v[102:105], v[144:147], v[200:203], v[102:105]
	v_mfma_f32_16x16x32_bf16 v[94:97], v[152:155], v[200:203], v[94:97]
	v_mfma_f32_16x16x32_bf16 v[86:89], v[144:147], v[208:211], v[86:89]
	v_mfma_f32_16x16x32_bf16 v[78:81], v[152:155], v[208:211], v[78:81]
	v_mfma_f32_16x16x32_bf16 v[126:129], v[148:151], v[188:191], v[126:129]
	v_mfma_f32_16x16x32_bf16 v[122:125], v[156:159], v[188:191], v[122:125]
	v_mfma_f32_16x16x32_bf16 v[118:121], v[148:151], v[196:199], v[118:121]
	v_mfma_f32_16x16x32_bf16 v[110:113], v[156:159], v[196:199], v[110:113]
	v_mfma_f32_16x16x32_bf16 v[102:105], v[148:151], v[204:207], v[102:105]
	v_mfma_f32_16x16x32_bf16 v[94:97], v[156:159], v[204:207], v[94:97]
	v_mfma_f32_16x16x32_bf16 v[86:89], v[148:151], v[212:215], v[86:89]
	v_mfma_f32_16x16x32_bf16 v[78:81], v[156:159], v[212:215], v[78:81]
	s_setprio 0
	s_setprio 1
	v_mfma_f32_16x16x32_bf16 v[114:117], v[160:163], v[184:187], v[114:117]
	v_mfma_f32_16x16x32_bf16 v[106:109], v[168:171], v[184:187], v[106:109]
	v_mfma_f32_16x16x32_bf16 v[98:101], v[160:163], v[192:195], v[98:101]
	v_mfma_f32_16x16x32_bf16 v[90:93], v[168:171], v[192:195], v[90:93]
	v_mfma_f32_16x16x32_bf16 v[82:85], v[160:163], v[200:203], v[82:85]
	v_mfma_f32_16x16x32_bf16 v[74:77], v[168:171], v[200:203], v[74:77]
	v_mfma_f32_16x16x32_bf16 v[70:73], v[160:163], v[208:211], v[70:73]
	v_mfma_f32_16x16x32_bf16 v[66:69], v[168:171], v[208:211], v[66:69]
	v_mfma_f32_16x16x32_bf16 v[114:117], v[164:167], v[188:191], v[114:117]
	v_mfma_f32_16x16x32_bf16 v[106:109], v[172:175], v[188:191], v[106:109]
	v_mfma_f32_16x16x32_bf16 v[98:101], v[164:167], v[196:199], v[98:101]
	v_mfma_f32_16x16x32_bf16 v[90:93], v[172:175], v[196:199], v[90:93]
	v_mfma_f32_16x16x32_bf16 v[82:85], v[164:167], v[204:207], v[82:85]
	v_mfma_f32_16x16x32_bf16 v[74:77], v[172:175], v[204:207], v[74:77]
	v_mfma_f32_16x16x32_bf16 v[70:73], v[164:167], v[212:215], v[70:73]
	v_mfma_f32_16x16x32_bf16 v[66:69], v[172:175], v[212:215], v[66:69]
	s_setprio 0
	s_barrier
	s_add_i32 s19, s45, s21
	v_lshl_add_u64 v[176:177], s[46:47], 0, v[0:1]
	s_mov_b32 m0, s19
	ds_read_b128 v[184:187], v143 offset:16384
	ds_read_b128 v[188:191], v143 offset:17408
	ds_read_b128 v[192:195], v143 offset:18432
	ds_read_b128 v[196:199], v143 offset:19456
	ds_read_b128 v[200:203], v143 offset:20480
	ds_read_b128 v[204:207], v143 offset:21504
	ds_read_b128 v[208:211], v143 offset:22528
	ds_read_b128 v[212:215], v143 offset:23552
	global_load_lds_dwordx4 v[176:177], off
	s_add_i32 m0, s19, 0x2000
	v_lshl_add_u64 v[216:217], s[46:47], 0, v[134:135]
	s_add_u32 s46, s46, s5
	s_addc_u32 s47, s47, 0
	s_add_i32 s18, s18, s21
	global_load_lds_dwordx4 v[216:217], off
	v_lshl_add_u64 v[218:219], s[46:47], 0, v[0:1]
	s_mov_b32 m0, s18
	v_lshl_add_u64 v[220:221], s[46:47], 0, v[134:135]
	global_load_lds_dwordx4 v[218:219], off
	s_add_i32 m0, s18, 0x2000
	v_lshl_add_u64 v[222:223], s[16:17], 0, v[130:131]
	global_load_lds_dwordx4 v[220:221], off
	s_mov_b32 m0, s22
	v_lshl_add_u64 v[224:225], s[16:17], 0, v[132:133]
	global_load_lds_dwordx4 v[222:223], off
	s_mov_b32 m0, s33
	s_nop 0
	global_load_lds_dwordx4 v[224:225], off
	s_waitcnt vmcnt(8)
	s_waitcnt lgkmcnt(0)
	s_barrier
	s_setprio 1
	s_waitcnt lgkmcnt(0)
	v_mfma_f32_16x16x32_bf16 v[62:65], v[144:147], v[184:187], v[62:65]
	v_mfma_f32_16x16x32_bf16 v[58:61], v[152:155], v[184:187], v[58:61]
	v_mfma_f32_16x16x32_bf16 v[54:57], v[144:147], v[192:195], v[54:57]
	v_mfma_f32_16x16x32_bf16 v[50:53], v[152:155], v[192:195], v[50:53]
	v_mfma_f32_16x16x32_bf16 v[38:41], v[144:147], v[200:203], v[38:41]
	v_mfma_f32_16x16x32_bf16 v[34:37], v[152:155], v[200:203], v[34:37]
	v_mfma_f32_16x16x32_bf16 v[22:25], v[144:147], v[208:211], v[22:25]
	v_mfma_f32_16x16x32_bf16 v[18:21], v[152:155], v[208:211], v[18:21]
	v_mfma_f32_16x16x32_bf16 v[62:65], v[148:151], v[188:191], v[62:65]
	v_mfma_f32_16x16x32_bf16 v[58:61], v[156:159], v[188:191], v[58:61]
	v_mfma_f32_16x16x32_bf16 v[54:57], v[148:151], v[196:199], v[54:57]
	v_mfma_f32_16x16x32_bf16 v[50:53], v[156:159], v[196:199], v[50:53]
	v_mfma_f32_16x16x32_bf16 v[38:41], v[148:151], v[204:207], v[38:41]
	v_mfma_f32_16x16x32_bf16 v[34:37], v[156:159], v[204:207], v[34:37]
	v_mfma_f32_16x16x32_bf16 v[22:25], v[148:151], v[212:215], v[22:25]
	v_mfma_f32_16x16x32_bf16 v[18:21], v[156:159], v[212:215], v[18:21]
	s_setprio 0
	s_setprio 1
	v_mfma_f32_16x16x32_bf16 v[46:49], v[160:163], v[184:187], v[46:49]
	v_mfma_f32_16x16x32_bf16 v[42:45], v[168:171], v[184:187], v[42:45]
	v_mfma_f32_16x16x32_bf16 v[30:33], v[160:163], v[192:195], v[30:33]
	v_mfma_f32_16x16x32_bf16 v[26:29], v[168:171], v[192:195], v[26:29]
	v_mfma_f32_16x16x32_bf16 v[14:17], v[160:163], v[200:203], v[14:17]
	v_mfma_f32_16x16x32_bf16 v[10:13], v[168:171], v[200:203], v[10:13]
	v_mfma_f32_16x16x32_bf16 v[6:9], v[160:163], v[208:211], v[6:9]
	v_mfma_f32_16x16x32_bf16 v[2:5], v[168:171], v[208:211], v[2:5]
	v_mfma_f32_16x16x32_bf16 v[46:49], v[164:167], v[188:191], v[46:49]
	v_mfma_f32_16x16x32_bf16 v[42:45], v[172:175], v[188:191], v[42:45]
	v_mfma_f32_16x16x32_bf16 v[30:33], v[164:167], v[196:199], v[30:33]
	v_mfma_f32_16x16x32_bf16 v[26:29], v[172:175], v[196:199], v[26:29]
	v_mfma_f32_16x16x32_bf16 v[14:17], v[164:167], v[204:207], v[14:17]
	v_mfma_f32_16x16x32_bf16 v[10:13], v[172:175], v[204:207], v[10:13]
	v_mfma_f32_16x16x32_bf16 v[6:9], v[164:167], v[212:215], v[6:9]
	v_mfma_f32_16x16x32_bf16 v[2:5], v[172:175], v[212:215], v[2:5]
	s_setprio 0
	s_barrier
	s_add_i32 s18, 0, 0x18000
	s_add_i32 s19, 0, 0x1c000
	v_add_u32_e32 v156, s18, v142
	v_add_u32_e32 v172, s19, v142
	ds_read_b128 v[144:147], v156
	ds_read_b128 v[148:151], v156 offset:1024
	ds_read_b128 v[152:155], v156 offset:2048
	ds_read_b128 v[156:159], v156 offset:3072
	ds_read_b128 v[160:163], v172
	ds_read_b128 v[164:167], v172 offset:1024
	ds_read_b128 v[168:171], v172 offset:2048
	ds_read_b128 v[172:175], v172 offset:3072
	s_add_u32 s16, s16, s10
	s_addc_u32 s17, s17, s11
	s_mov_b32 m0, s36
	v_lshl_add_u64 v[226:227], s[16:17], 0, v[130:131]
	ds_read_b128 v[184:187], v143 offset:32768
	ds_read_b128 v[188:191], v143 offset:33792
	ds_read_b128 v[192:195], v143 offset:34816
	ds_read_b128 v[196:199], v143 offset:35840
	ds_read_b128 v[200:203], v143 offset:36864
	ds_read_b128 v[204:207], v143 offset:37888
	ds_read_b128 v[208:211], v143 offset:38912
	ds_read_b128 v[212:215], v143 offset:39936
	global_load_lds_dwordx4 v[226:227], off
	v_lshl_add_u64 v[226:227], s[16:17], 0, v[132:133]
	s_mov_b32 m0, s37
	s_nop 0
	global_load_lds_dwordx4 v[226:227], off
	s_waitcnt vmcnt(8)
	s_waitcnt lgkmcnt(0)
	s_barrier
	s_setprio 1
	s_waitcnt lgkmcnt(0)
	v_mfma_f32_16x16x32_bf16 v[126:129], v[144:147], v[184:187], v[126:129]
	v_mfma_f32_16x16x32_bf16 v[122:125], v[152:155], v[184:187], v[122:125]
	v_mfma_f32_16x16x32_bf16 v[118:121], v[144:147], v[192:195], v[118:121]
	v_mfma_f32_16x16x32_bf16 v[110:113], v[152:155], v[192:195], v[110:113]
	v_mfma_f32_16x16x32_bf16 v[102:105], v[144:147], v[200:203], v[102:105]
	v_mfma_f32_16x16x32_bf16 v[94:97], v[152:155], v[200:203], v[94:97]
	v_mfma_f32_16x16x32_bf16 v[86:89], v[144:147], v[208:211], v[86:89]
	v_mfma_f32_16x16x32_bf16 v[78:81], v[152:155], v[208:211], v[78:81]
	v_mfma_f32_16x16x32_bf16 v[126:129], v[148:151], v[188:191], v[126:129]
	v_mfma_f32_16x16x32_bf16 v[122:125], v[156:159], v[188:191], v[122:125]
	v_mfma_f32_16x16x32_bf16 v[118:121], v[148:151], v[196:199], v[118:121]
	v_mfma_f32_16x16x32_bf16 v[110:113], v[156:159], v[196:199], v[110:113]
	v_mfma_f32_16x16x32_bf16 v[102:105], v[148:151], v[204:207], v[102:105]
	v_mfma_f32_16x16x32_bf16 v[94:97], v[156:159], v[204:207], v[94:97]
	v_mfma_f32_16x16x32_bf16 v[86:89], v[148:151], v[212:215], v[86:89]
	v_mfma_f32_16x16x32_bf16 v[78:81], v[156:159], v[212:215], v[78:81]
	s_setprio 0
	s_setprio 1
	v_mfma_f32_16x16x32_bf16 v[114:117], v[160:163], v[184:187], v[114:117]
	v_mfma_f32_16x16x32_bf16 v[106:109], v[168:171], v[184:187], v[106:109]
	v_mfma_f32_16x16x32_bf16 v[98:101], v[160:163], v[192:195], v[98:101]
	v_mfma_f32_16x16x32_bf16 v[90:93], v[168:171], v[192:195], v[90:93]
	v_mfma_f32_16x16x32_bf16 v[82:85], v[160:163], v[200:203], v[82:85]
	v_mfma_f32_16x16x32_bf16 v[74:77], v[168:171], v[200:203], v[74:77]
	v_mfma_f32_16x16x32_bf16 v[70:73], v[160:163], v[208:211], v[70:73]
	v_mfma_f32_16x16x32_bf16 v[66:69], v[168:171], v[208:211], v[66:69]
	v_mfma_f32_16x16x32_bf16 v[114:117], v[164:167], v[188:191], v[114:117]
	v_mfma_f32_16x16x32_bf16 v[106:109], v[172:175], v[188:191], v[106:109]
	v_mfma_f32_16x16x32_bf16 v[98:101], v[164:167], v[196:199], v[98:101]
	v_mfma_f32_16x16x32_bf16 v[90:93], v[172:175], v[196:199], v[90:93]
	v_mfma_f32_16x16x32_bf16 v[82:85], v[164:167], v[204:207], v[82:85]
	v_mfma_f32_16x16x32_bf16 v[74:77], v[172:175], v[204:207], v[74:77]
	v_mfma_f32_16x16x32_bf16 v[70:73], v[164:167], v[212:215], v[70:73]
	v_mfma_f32_16x16x32_bf16 v[66:69], v[172:175], v[212:215], v[66:69]
	s_setprio 0
	s_barrier
	s_add_i32 s16, s18, s21
	v_lshl_add_u64 v[176:177], v[176:177], 0, s[90:91]
	s_mov_b32 m0, s16
	ds_read_b128 v[184:187], v143 offset:49152
	ds_read_b128 v[188:191], v143 offset:50176
	ds_read_b128 v[192:195], v143 offset:51200
	ds_read_b128 v[196:199], v143 offset:52224
	ds_read_b128 v[200:203], v143 offset:53248
	ds_read_b128 v[204:207], v143 offset:54272
	ds_read_b128 v[208:211], v143 offset:55296
	ds_read_b128 v[212:215], v143 offset:56320
	global_load_lds_dwordx4 v[176:177], off
	v_lshl_add_u64 v[176:177], v[216:217], 0, s[90:91]
	s_add_i32 m0, s16, 0x2000
	s_add_i32 s16, s19, s21
	global_load_lds_dwordx4 v[176:177], off
	v_lshl_add_u64 v[176:177], v[218:219], 0, s[90:91]
	s_mov_b32 m0, s16
	s_nop 0
	global_load_lds_dwordx4 v[176:177], off
	v_lshl_add_u64 v[176:177], v[220:221], 0, s[90:91]
	s_add_i32 m0, s16, 0x2000
	s_nop 0
	global_load_lds_dwordx4 v[176:177], off
	v_lshl_add_u64 v[176:177], v[222:223], 0, s[90:91]
	s_mov_b32 m0, s41
	s_nop 0
	global_load_lds_dwordx4 v[176:177], off
	v_lshl_add_u64 v[176:177], v[224:225], 0, s[90:91]
	s_mov_b32 m0, s42
	s_nop 0
	global_load_lds_dwordx4 v[176:177], off
	s_waitcnt vmcnt(8)
	s_waitcnt lgkmcnt(0)
	s_barrier
	s_setprio 1
	s_waitcnt lgkmcnt(0)
	v_mfma_f32_16x16x32_bf16 v[62:65], v[144:147], v[184:187], v[62:65]
	v_mfma_f32_16x16x32_bf16 v[58:61], v[152:155], v[184:187], v[58:61]
	v_mfma_f32_16x16x32_bf16 v[54:57], v[144:147], v[192:195], v[54:57]
	v_mfma_f32_16x16x32_bf16 v[50:53], v[152:155], v[192:195], v[50:53]
	v_mfma_f32_16x16x32_bf16 v[38:41], v[144:147], v[200:203], v[38:41]
	v_mfma_f32_16x16x32_bf16 v[34:37], v[152:155], v[200:203], v[34:37]
	v_mfma_f32_16x16x32_bf16 v[22:25], v[144:147], v[208:211], v[22:25]
	v_mfma_f32_16x16x32_bf16 v[18:21], v[152:155], v[208:211], v[18:21]
	v_mfma_f32_16x16x32_bf16 v[62:65], v[148:151], v[188:191], v[62:65]
	v_mfma_f32_16x16x32_bf16 v[58:61], v[156:159], v[188:191], v[58:61]
	v_mfma_f32_16x16x32_bf16 v[54:57], v[148:151], v[196:199], v[54:57]
	v_mfma_f32_16x16x32_bf16 v[50:53], v[156:159], v[196:199], v[50:53]
	v_mfma_f32_16x16x32_bf16 v[38:41], v[148:151], v[204:207], v[38:41]
	v_mfma_f32_16x16x32_bf16 v[34:37], v[156:159], v[204:207], v[34:37]
	v_mfma_f32_16x16x32_bf16 v[22:25], v[148:151], v[212:215], v[22:25]
	v_mfma_f32_16x16x32_bf16 v[18:21], v[156:159], v[212:215], v[18:21]
	s_setprio 0
	s_setprio 1
	v_mfma_f32_16x16x32_bf16 v[46:49], v[160:163], v[184:187], v[46:49]
	v_mfma_f32_16x16x32_bf16 v[42:45], v[168:171], v[184:187], v[42:45]
	v_mfma_f32_16x16x32_bf16 v[30:33], v[160:163], v[192:195], v[30:33]
	v_mfma_f32_16x16x32_bf16 v[26:29], v[168:171], v[192:195], v[26:29]
	v_mfma_f32_16x16x32_bf16 v[14:17], v[160:163], v[200:203], v[14:17]
	v_mfma_f32_16x16x32_bf16 v[10:13], v[168:171], v[200:203], v[10:13]
	v_mfma_f32_16x16x32_bf16 v[6:9], v[160:163], v[208:211], v[6:9]
	v_mfma_f32_16x16x32_bf16 v[2:5], v[168:171], v[208:211], v[2:5]
	v_mfma_f32_16x16x32_bf16 v[46:49], v[164:167], v[188:191], v[46:49]
	v_mfma_f32_16x16x32_bf16 v[42:45], v[172:175], v[188:191], v[42:45]
	v_mfma_f32_16x16x32_bf16 v[30:33], v[164:167], v[196:199], v[30:33]
	v_mfma_f32_16x16x32_bf16 v[26:29], v[172:175], v[196:199], v[26:29]
	v_mfma_f32_16x16x32_bf16 v[14:17], v[164:167], v[204:207], v[14:17]
	v_mfma_f32_16x16x32_bf16 v[10:13], v[172:175], v[204:207], v[10:13]
	v_mfma_f32_16x16x32_bf16 v[6:9], v[164:167], v[212:215], v[6:9]
	v_mfma_f32_16x16x32_bf16 v[2:5], v[172:175], v[212:215], v[2:5]
	s_setprio 0
	s_add_u32 s14, s14, 0x100
	s_addc_u32 s15, s15, 0
	s_cmp_ge_u32 s44, s40
	s_mov_b32 s16, s44
	s_barrier
	s_cbranch_scc0 .LBB0_615
	s_cmpk_lt_u32 s4, 0x100
	s_cbranch_scc0 .LBB0_602
	s_barrier
	s_branch .LBB0_602

.LBB0_822:
	s_cmp_eq_u32 s85, s44
	s_cselect_b64 s[46:47], -1, 0
	s_add_i32 vcc_lo, vcc_lo, 2
	s_add_u32 s18, s40, s44
	s_addc_u32 s19, s41, s45
	s_add_u32 s18, s18, 0x100
	s_addc_u32 s19, s19, 0
	s_and_b64 s[48:49], s[46:47], exec
	s_cselect_b32 s49, s67, s19
	s_cselect_b32 s48, s74, s18
	s_and_b64 s[18:19], s[42:43], s[46:47]
	s_and_b64 s[18:19], s[18:19], exec
	s_cselect_b32 s25, 0, s39
	s_cselect_b32 vcc_hi, 0x80000, s38
	s_add_i32 s69, 0, 0x10000
	s_add_u32 s24, s92, s44
	s_addc_u32 s20, s93, s45
	s_and_b64 s[18:19], s[46:47], exec
	s_cselect_b32 s47, s75, s20
	s_cselect_b32 s46, s79, s24
	s_add_i32 s20, 0, 0x14000
	v_add_u32_e32 v146, s69, v202
	v_add_u32_e32 v162, s20, v202
	ds_read_b128 v[118:121], v146
	ds_read_b128 v[122:125], v146 offset:1024
	ds_read_b128 v[126:129], v146 offset:2048
	ds_read_b128 v[146:149], v146 offset:3072
	ds_read_b128 v[150:153], v162
	ds_read_b128 v[154:157], v162 offset:1024
	ds_read_b128 v[158:161], v162 offset:2048
	ds_read_b128 v[162:165], v162 offset:3072
	v_lshl_add_u64 v[198:199], v[110:111], 0, s[44:45]
	s_add_i32 m0, s54, 0xc000
	ds_read_b128 v[166:169], v203
	ds_read_b128 v[170:173], v203 offset:1024
	ds_read_b128 v[174:177], v203 offset:2048
	ds_read_b128 v[194:197], v203 offset:3072
	ds_read_b128 v[204:207], v203 offset:4096
	ds_read_b128 v[208:211], v203 offset:5120
	ds_read_b128 v[212:215], v203 offset:6144
	ds_read_b128 v[216:219], v203 offset:7168
	global_load_lds_dwordx4 v[198:199], off
	v_lshl_add_u64 v[198:199], v[112:113], 0, s[44:45]
	s_add_i32 m0, s54, 0xe000
	s_nop 0
	global_load_lds_dwordx4 v[198:199], off
	s_waitcnt vmcnt(8)
	s_waitcnt lgkmcnt(0)
	s_barrier
	s_setprio 1
	s_waitcnt lgkmcnt(0)
	v_mfma_f32_16x16x32_bf16 v[142:145], v[118:121], v[166:169], v[142:145]
	v_mfma_f32_16x16x32_bf16 v[138:141], v[126:129], v[166:169], v[138:141]
	v_mfma_f32_16x16x32_bf16 v[114:117], v[118:121], v[174:177], v[114:117]
	v_mfma_f32_16x16x32_bf16 v[106:109], v[126:129], v[174:177], v[106:109]
	v_mfma_f32_16x16x32_bf16 v[94:97], v[118:121], v[204:207], v[94:97]
	v_mfma_f32_16x16x32_bf16 v[90:93], v[126:129], v[204:207], v[90:93]
	v_mfma_f32_16x16x32_bf16 v[78:81], v[118:121], v[212:215], v[78:81]
	v_mfma_f32_16x16x32_bf16 v[74:77], v[126:129], v[212:215], v[74:77]
	v_mfma_f32_16x16x32_bf16 v[142:145], v[122:125], v[170:173], v[142:145]
	v_mfma_f32_16x16x32_bf16 v[138:141], v[146:149], v[170:173], v[138:141]
	v_mfma_f32_16x16x32_bf16 v[114:117], v[122:125], v[194:197], v[114:117]
	v_mfma_f32_16x16x32_bf16 v[106:109], v[146:149], v[194:197], v[106:109]
	v_mfma_f32_16x16x32_bf16 v[94:97], v[122:125], v[208:211], v[94:97]
	v_mfma_f32_16x16x32_bf16 v[90:93], v[146:149], v[208:211], v[90:93]
	v_mfma_f32_16x16x32_bf16 v[78:81], v[122:125], v[216:219], v[78:81]
	v_mfma_f32_16x16x32_bf16 v[74:77], v[146:149], v[216:219], v[74:77]
	s_setprio 0
	s_setprio 1
	v_mfma_f32_16x16x32_bf16 v[134:137], v[150:153], v[166:169], v[134:137]
	v_mfma_f32_16x16x32_bf16 v[130:133], v[158:161], v[166:169], v[130:133]
	v_mfma_f32_16x16x32_bf16 v[102:105], v[150:153], v[174:177], v[102:105]
	v_mfma_f32_16x16x32_bf16 v[98:101], v[158:161], v[174:177], v[98:101]
	v_mfma_f32_16x16x32_bf16 v[86:89], v[150:153], v[204:207], v[86:89]
	v_mfma_f32_16x16x32_bf16 v[82:85], v[158:161], v[204:207], v[82:85]
	v_mfma_f32_16x16x32_bf16 v[70:73], v[150:153], v[212:215], v[70:73]
	v_mfma_f32_16x16x32_bf16 v[66:69], v[158:161], v[212:215], v[66:69]
	v_mfma_f32_16x16x32_bf16 v[134:137], v[154:157], v[170:173], v[134:137]
	v_mfma_f32_16x16x32_bf16 v[130:133], v[162:165], v[170:173], v[130:133]
	v_mfma_f32_16x16x32_bf16 v[102:105], v[154:157], v[194:197], v[102:105]
	v_mfma_f32_16x16x32_bf16 v[98:101], v[162:165], v[194:197], v[98:101]
	v_mfma_f32_16x16x32_bf16 v[86:89], v[154:157], v[208:211], v[86:89]
	v_mfma_f32_16x16x32_bf16 v[82:85], v[162:165], v[208:211], v[82:85]
	v_mfma_f32_16x16x32_bf16 v[70:73], v[154:157], v[216:219], v[70:73]
	v_mfma_f32_16x16x32_bf16 v[66:69], v[162:165], v[216:219], v[66:69]
	s_setprio 0
	s_barrier
	s_add_i32 s18, s69, s53
	v_lshl_add_u64 v[198:199], s[46:47], 0, v[0:1]
	s_mov_b32 m0, s18
	ds_read_b128 v[166:169], v203 offset:16384
	ds_read_b128 v[170:173], v203 offset:17408
	ds_read_b128 v[174:177], v203 offset:18432
	ds_read_b128 v[194:197], v203 offset:19456
	ds_read_b128 v[204:207], v203 offset:20480
	ds_read_b128 v[208:211], v203 offset:21504
	ds_read_b128 v[212:215], v203 offset:22528
	ds_read_b128 v[216:219], v203 offset:23552
	global_load_lds_dwordx4 v[198:199], off
	s_add_i32 m0, s18, 0x2000
	s_add_u32 s18, s46, 0x80000
	v_lshl_add_u64 v[220:221], s[46:47], 0, v[188:189]
	s_addc_u32 s19, s47, 0
	s_add_i32 s20, s20, s53
	global_load_lds_dwordx4 v[220:221], off
	v_lshl_add_u64 v[222:223], s[18:19], 0, v[0:1]
	s_mov_b32 m0, s20
	v_lshl_add_u64 v[224:225], s[48:49], 0, v[186:187]
	global_load_lds_dwordx4 v[222:223], off
	v_lshl_add_u64 v[222:223], s[18:19], 0, v[188:189]
	s_add_i32 m0, s20, 0x2000
	s_nop 0
	global_load_lds_dwordx4 v[222:223], off
	v_lshl_add_u64 v[222:223], s[48:49], 0, v[184:185]
	s_mov_b32 m0, s54
	s_nop 0
	global_load_lds_dwordx4 v[222:223], off
	s_mov_b32 m0, s55
	s_nop 0
	global_load_lds_dwordx4 v[224:225], off
	s_waitcnt vmcnt(8)
	s_waitcnt lgkmcnt(0)
	s_barrier
	s_setprio 1
	s_waitcnt lgkmcnt(0)
	v_mfma_f32_16x16x32_bf16 v[62:65], v[118:121], v[166:169], v[62:65]
	v_mfma_f32_16x16x32_bf16 v[58:61], v[126:129], v[166:169], v[58:61]
	v_mfma_f32_16x16x32_bf16 v[46:49], v[118:121], v[174:177], v[46:49]
	v_mfma_f32_16x16x32_bf16 v[42:45], v[126:129], v[174:177], v[42:45]
	v_mfma_f32_16x16x32_bf16 v[30:33], v[118:121], v[204:207], v[30:33]
	v_mfma_f32_16x16x32_bf16 v[26:29], v[126:129], v[204:207], v[26:29]
	v_mfma_f32_16x16x32_bf16 v[14:17], v[118:121], v[212:215], v[14:17]
	v_mfma_f32_16x16x32_bf16 v[10:13], v[126:129], v[212:215], v[10:13]
	v_mfma_f32_16x16x32_bf16 v[62:65], v[122:125], v[170:173], v[62:65]
	v_mfma_f32_16x16x32_bf16 v[58:61], v[146:149], v[170:173], v[58:61]
	v_mfma_f32_16x16x32_bf16 v[46:49], v[122:125], v[194:197], v[46:49]
	v_mfma_f32_16x16x32_bf16 v[42:45], v[146:149], v[194:197], v[42:45]
	v_mfma_f32_16x16x32_bf16 v[30:33], v[122:125], v[208:211], v[30:33]
	v_mfma_f32_16x16x32_bf16 v[26:29], v[146:149], v[208:211], v[26:29]
	v_mfma_f32_16x16x32_bf16 v[14:17], v[122:125], v[216:219], v[14:17]
	v_mfma_f32_16x16x32_bf16 v[10:13], v[146:149], v[216:219], v[10:13]
	s_setprio 0
	s_setprio 1
	v_mfma_f32_16x16x32_bf16 v[54:57], v[150:153], v[166:169], v[54:57]
	v_mfma_f32_16x16x32_bf16 v[50:53], v[158:161], v[166:169], v[50:53]
	v_mfma_f32_16x16x32_bf16 v[38:41], v[150:153], v[174:177], v[38:41]
	v_mfma_f32_16x16x32_bf16 v[34:37], v[158:161], v[174:177], v[34:37]
	v_mfma_f32_16x16x32_bf16 v[22:25], v[150:153], v[204:207], v[22:25]
	v_mfma_f32_16x16x32_bf16 v[18:21], v[158:161], v[204:207], v[18:21]
	v_mfma_f32_16x16x32_bf16 v[6:9], v[150:153], v[212:215], v[6:9]
	v_mfma_f32_16x16x32_bf16 v[2:5], v[158:161], v[212:215], v[2:5]
	v_mfma_f32_16x16x32_bf16 v[54:57], v[154:157], v[170:173], v[54:57]
	v_mfma_f32_16x16x32_bf16 v[50:53], v[162:165], v[170:173], v[50:53]
	v_mfma_f32_16x16x32_bf16 v[38:41], v[154:157], v[194:197], v[38:41]
	v_mfma_f32_16x16x32_bf16 v[34:37], v[162:165], v[194:197], v[34:37]
	v_mfma_f32_16x16x32_bf16 v[22:25], v[154:157], v[208:211], v[22:25]
	v_mfma_f32_16x16x32_bf16 v[18:21], v[162:165], v[208:211], v[18:21]
	v_mfma_f32_16x16x32_bf16 v[6:9], v[154:157], v[216:219], v[6:9]
	v_mfma_f32_16x16x32_bf16 v[2:5], v[162:165], v[216:219], v[2:5]
	s_setprio 0
	s_barrier
	s_add_i32 s20, 0, 0x18000
	s_add_i32 s24, 0, 0x1c000
	v_add_u32_e32 v146, s20, v202
	v_add_u32_e32 v162, s24, v202
	ds_read_b128 v[118:121], v146
	ds_read_b128 v[122:125], v146 offset:1024
	ds_read_b128 v[126:129], v146 offset:2048
	ds_read_b128 v[146:149], v146 offset:3072
	ds_read_b128 v[150:153], v162
	ds_read_b128 v[154:157], v162 offset:1024
	ds_read_b128 v[158:161], v162 offset:2048
	ds_read_b128 v[162:165], v162 offset:3072
	s_add_u32 s18, s48, vcc_hi
	s_addc_u32 s19, s49, s25
	s_mov_b32 m0, s56
	v_lshl_add_u64 v[226:227], s[18:19], 0, v[184:185]
	ds_read_b128 v[166:169], v203 offset:32768
	ds_read_b128 v[170:173], v203 offset:33792
	ds_read_b128 v[174:177], v203 offset:34816
	ds_read_b128 v[194:197], v203 offset:35840
	ds_read_b128 v[204:207], v203 offset:36864
	ds_read_b128 v[208:211], v203 offset:37888
	ds_read_b128 v[212:215], v203 offset:38912
	ds_read_b128 v[216:219], v203 offset:39936
	global_load_lds_dwordx4 v[226:227], off
	v_lshl_add_u64 v[226:227], s[18:19], 0, v[186:187]
	s_mov_b32 m0, s57
	s_nop 0
	global_load_lds_dwordx4 v[226:227], off
	s_waitcnt vmcnt(8)
	s_waitcnt lgkmcnt(0)
	s_barrier
	s_setprio 1
	s_waitcnt lgkmcnt(0)
	v_mfma_f32_16x16x32_bf16 v[142:145], v[118:121], v[166:169], v[142:145]
	v_mfma_f32_16x16x32_bf16 v[138:141], v[126:129], v[166:169], v[138:141]
	v_mfma_f32_16x16x32_bf16 v[114:117], v[118:121], v[174:177], v[114:117]
	v_mfma_f32_16x16x32_bf16 v[106:109], v[126:129], v[174:177], v[106:109]
	v_mfma_f32_16x16x32_bf16 v[94:97], v[118:121], v[204:207], v[94:97]
	v_mfma_f32_16x16x32_bf16 v[90:93], v[126:129], v[204:207], v[90:93]
	v_mfma_f32_16x16x32_bf16 v[78:81], v[118:121], v[212:215], v[78:81]
	v_mfma_f32_16x16x32_bf16 v[74:77], v[126:129], v[212:215], v[74:77]
	v_mfma_f32_16x16x32_bf16 v[142:145], v[122:125], v[170:173], v[142:145]
	v_mfma_f32_16x16x32_bf16 v[138:141], v[146:149], v[170:173], v[138:141]
	v_mfma_f32_16x16x32_bf16 v[114:117], v[122:125], v[194:197], v[114:117]
	v_mfma_f32_16x16x32_bf16 v[106:109], v[146:149], v[194:197], v[106:109]
	v_mfma_f32_16x16x32_bf16 v[94:97], v[122:125], v[208:211], v[94:97]
	v_mfma_f32_16x16x32_bf16 v[90:93], v[146:149], v[208:211], v[90:93]
	v_mfma_f32_16x16x32_bf16 v[78:81], v[122:125], v[216:219], v[78:81]
	v_mfma_f32_16x16x32_bf16 v[74:77], v[146:149], v[216:219], v[74:77]
	s_setprio 0
	s_setprio 1
	v_mfma_f32_16x16x32_bf16 v[134:137], v[150:153], v[166:169], v[134:137]
	v_mfma_f32_16x16x32_bf16 v[130:133], v[158:161], v[166:169], v[130:133]
	v_mfma_f32_16x16x32_bf16 v[102:105], v[150:153], v[174:177], v[102:105]
	v_mfma_f32_16x16x32_bf16 v[98:101], v[158:161], v[174:177], v[98:101]
	v_mfma_f32_16x16x32_bf16 v[86:89], v[150:153], v[204:207], v[86:89]
	v_mfma_f32_16x16x32_bf16 v[82:85], v[158:161], v[204:207], v[82:85]
	v_mfma_f32_16x16x32_bf16 v[70:73], v[150:153], v[212:215], v[70:73]
	v_mfma_f32_16x16x32_bf16 v[66:69], v[158:161], v[212:215], v[66:69]
	v_mfma_f32_16x16x32_bf16 v[134:137], v[154:157], v[170:173], v[134:137]
	v_mfma_f32_16x16x32_bf16 v[130:133], v[162:165], v[170:173], v[130:133]
	v_mfma_f32_16x16x32_bf16 v[102:105], v[154:157], v[194:197], v[102:105]
	v_mfma_f32_16x16x32_bf16 v[98:101], v[162:165], v[194:197], v[98:101]
	v_mfma_f32_16x16x32_bf16 v[86:89], v[154:157], v[208:211], v[86:89]
	v_mfma_f32_16x16x32_bf16 v[82:85], v[162:165], v[208:211], v[82:85]
	v_mfma_f32_16x16x32_bf16 v[70:73], v[154:157], v[216:219], v[70:73]
	v_mfma_f32_16x16x32_bf16 v[66:69], v[162:165], v[216:219], v[66:69]
	s_setprio 0
	s_barrier
	s_add_i32 s18, s20, s53
	v_lshl_add_u64 v[198:199], v[198:199], 0, s[90:91]
	s_mov_b32 m0, s18
	ds_read_b128 v[166:169], v203 offset:49152
	ds_read_b128 v[170:173], v203 offset:50176
	ds_read_b128 v[174:177], v203 offset:51200
	ds_read_b128 v[194:197], v203 offset:52224
	ds_read_b128 v[204:207], v203 offset:53248
	ds_read_b128 v[208:211], v203 offset:54272
	ds_read_b128 v[212:215], v203 offset:55296
	ds_read_b128 v[216:219], v203 offset:56320
	global_load_lds_dwordx4 v[198:199], off
	s_add_i32 m0, s18, 0x2000
	s_add_u32 s18, s46, 0x80080
	v_lshl_add_u64 v[198:199], v[220:221], 0, s[90:91]
	s_addc_u32 s19, s47, 0
	s_add_i32 s20, s24, s53
	global_load_lds_dwordx4 v[198:199], off
	v_lshl_add_u64 v[198:199], s[18:19], 0, v[0:1]
	s_mov_b32 m0, s20
	s_nop 0
	global_load_lds_dwordx4 v[198:199], off
	v_lshl_add_u64 v[198:199], s[18:19], 0, v[188:189]
	s_add_i32 m0, s20, 0x2000
	s_nop 0
	global_load_lds_dwordx4 v[198:199], off
	v_lshl_add_u64 v[198:199], v[222:223], 0, s[90:91]
	s_mov_b32 m0, s82
	s_nop 0
	global_load_lds_dwordx4 v[198:199], off
	v_lshl_add_u64 v[198:199], v[224:225], 0, s[90:91]
	s_mov_b32 m0, s83
	s_nop 0
	global_load_lds_dwordx4 v[198:199], off
	s_waitcnt vmcnt(8)
	s_waitcnt lgkmcnt(0)
	s_barrier
	s_setprio 1
	s_waitcnt lgkmcnt(0)
	v_mfma_f32_16x16x32_bf16 v[62:65], v[118:121], v[166:169], v[62:65]
	v_mfma_f32_16x16x32_bf16 v[58:61], v[126:129], v[166:169], v[58:61]
	v_mfma_f32_16x16x32_bf16 v[46:49], v[118:121], v[174:177], v[46:49]
	v_mfma_f32_16x16x32_bf16 v[42:45], v[126:129], v[174:177], v[42:45]
	v_mfma_f32_16x16x32_bf16 v[30:33], v[118:121], v[204:207], v[30:33]
	v_mfma_f32_16x16x32_bf16 v[26:29], v[126:129], v[204:207], v[26:29]
	v_mfma_f32_16x16x32_bf16 v[14:17], v[118:121], v[212:215], v[14:17]
	v_mfma_f32_16x16x32_bf16 v[10:13], v[126:129], v[212:215], v[10:13]
	v_mfma_f32_16x16x32_bf16 v[62:65], v[122:125], v[170:173], v[62:65]
	v_mfma_f32_16x16x32_bf16 v[58:61], v[146:149], v[170:173], v[58:61]
	v_mfma_f32_16x16x32_bf16 v[46:49], v[122:125], v[194:197], v[46:49]
	v_mfma_f32_16x16x32_bf16 v[42:45], v[146:149], v[194:197], v[42:45]
	v_mfma_f32_16x16x32_bf16 v[30:33], v[122:125], v[208:211], v[30:33]
	v_mfma_f32_16x16x32_bf16 v[26:29], v[146:149], v[208:211], v[26:29]
	v_mfma_f32_16x16x32_bf16 v[14:17], v[122:125], v[216:219], v[14:17]
	v_mfma_f32_16x16x32_bf16 v[10:13], v[146:149], v[216:219], v[10:13]
	s_setprio 0
	s_setprio 1
	v_mfma_f32_16x16x32_bf16 v[54:57], v[150:153], v[166:169], v[54:57]
	v_mfma_f32_16x16x32_bf16 v[50:53], v[158:161], v[166:169], v[50:53]
	v_mfma_f32_16x16x32_bf16 v[38:41], v[150:153], v[174:177], v[38:41]
	v_mfma_f32_16x16x32_bf16 v[34:37], v[158:161], v[174:177], v[34:37]
	v_mfma_f32_16x16x32_bf16 v[22:25], v[150:153], v[204:207], v[22:25]
	v_mfma_f32_16x16x32_bf16 v[18:21], v[158:161], v[204:207], v[18:21]
	v_mfma_f32_16x16x32_bf16 v[6:9], v[150:153], v[212:215], v[6:9]
	v_mfma_f32_16x16x32_bf16 v[2:5], v[158:161], v[212:215], v[2:5]
	v_mfma_f32_16x16x32_bf16 v[54:57], v[154:157], v[170:173], v[54:57]
	v_mfma_f32_16x16x32_bf16 v[50:53], v[162:165], v[170:173], v[50:53]
	v_mfma_f32_16x16x32_bf16 v[38:41], v[154:157], v[194:197], v[38:41]
	v_mfma_f32_16x16x32_bf16 v[34:37], v[162:165], v[194:197], v[34:37]
	v_mfma_f32_16x16x32_bf16 v[22:25], v[154:157], v[208:211], v[22:25]
	v_mfma_f32_16x16x32_bf16 v[18:21], v[162:165], v[208:211], v[18:21]
	v_mfma_f32_16x16x32_bf16 v[6:9], v[154:157], v[216:219], v[6:9]
	v_mfma_f32_16x16x32_bf16 v[2:5], v[162:165], v[216:219], v[2:5]
	s_setprio 0
	s_add_u32 s44, s44, 0x100
	s_addc_u32 s45, s45, 0
	s_cmp_ge_u32 vcc_lo, s58
	s_barrier
	s_cbranch_scc0 .LBB0_822
	s_and_b64 vcc, exec, s[10:11]
	s_cbranch_vccz .LBB0_825
	s_barrier

.LBB0_1003:
	s_add_u32 s18, s42, 0xfff80080
	s_addc_u32 s19, s43, -1
	s_add_i32 s20, 0, 0x10000
	s_cmp_eq_u32 s59, 28
	s_cselect_b32 s47, s39, s19
	s_cselect_b32 s46, s38, s18
	v_add_u32_e32 v140, s20, v144
	s_cselect_b32 s45, s41, s58
	s_cselect_b32 s44, s40, s17
	s_add_i32 s24, 0, 0x14000
	ds_read_b128 v[146:149], v140
	ds_read_b128 v[150:153], v140 offset:1024
	ds_read_b128 v[154:157], v140 offset:2048
	ds_read_b128 v[158:161], v140 offset:3072
	v_add_u32_e32 v140, s24, v144
	ds_read_b128 v[162:165], v140
	ds_read_b128 v[166:169], v140 offset:1024
	ds_read_b128 v[170:173], v140 offset:2048
	ds_read_b128 v[174:177], v140 offset:3072
	v_lshl_add_u64 v[140:141], s[42:43], 0, v[136:137]
	s_add_i32 m0, s21, 0xc000
	ds_read_b128 v[184:187], v145
	ds_read_b128 v[188:191], v145 offset:1024
	ds_read_b128 v[192:195], v145 offset:2048
	ds_read_b128 v[196:199], v145 offset:3072
	ds_read_b128 v[200:203], v145 offset:4096
	ds_read_b128 v[204:207], v145 offset:5120
	ds_read_b128 v[208:211], v145 offset:6144
	ds_read_b128 v[212:215], v145 offset:7168
	global_load_lds_dwordx4 v[140:141], off
	v_lshl_add_u64 v[140:141], s[42:43], 0, v[138:139]
	s_add_i32 m0, s21, 0xe000
	s_nop 0
	global_load_lds_dwordx4 v[140:141], off
	s_waitcnt vmcnt(8)
	s_waitcnt lgkmcnt(0)
	s_barrier
	s_setprio 1
	s_waitcnt lgkmcnt(0)
	v_mfma_f32_16x16x32_bf16 v[126:129], v[146:149], v[184:187], v[126:129]
	v_mfma_f32_16x16x32_bf16 v[122:125], v[154:157], v[184:187], v[122:125]
	v_mfma_f32_16x16x32_bf16 v[110:113], v[146:149], v[192:195], v[110:113]
	v_mfma_f32_16x16x32_bf16 v[106:109], v[154:157], v[192:195], v[106:109]
	v_mfma_f32_16x16x32_bf16 v[94:97], v[146:149], v[200:203], v[94:97]
	v_mfma_f32_16x16x32_bf16 v[90:93], v[154:157], v[200:203], v[90:93]
	v_mfma_f32_16x16x32_bf16 v[78:81], v[146:149], v[208:211], v[78:81]
	v_mfma_f32_16x16x32_bf16 v[74:77], v[154:157], v[208:211], v[74:77]
	v_mfma_f32_16x16x32_bf16 v[126:129], v[150:153], v[188:191], v[126:129]
	v_mfma_f32_16x16x32_bf16 v[122:125], v[158:161], v[188:191], v[122:125]
	v_mfma_f32_16x16x32_bf16 v[110:113], v[150:153], v[196:199], v[110:113]
	v_mfma_f32_16x16x32_bf16 v[106:109], v[158:161], v[196:199], v[106:109]
	v_mfma_f32_16x16x32_bf16 v[94:97], v[150:153], v[204:207], v[94:97]
	v_mfma_f32_16x16x32_bf16 v[90:93], v[158:161], v[204:207], v[90:93]
	v_mfma_f32_16x16x32_bf16 v[78:81], v[150:153], v[212:215], v[78:81]
	v_mfma_f32_16x16x32_bf16 v[74:77], v[158:161], v[212:215], v[74:77]
	s_setprio 0
	s_setprio 1
	v_mfma_f32_16x16x32_bf16 v[118:121], v[162:165], v[184:187], v[118:121]
	v_mfma_f32_16x16x32_bf16 v[114:117], v[170:173], v[184:187], v[114:117]
	v_mfma_f32_16x16x32_bf16 v[102:105], v[162:165], v[192:195], v[102:105]
	v_mfma_f32_16x16x32_bf16 v[98:101], v[170:173], v[192:195], v[98:101]
	v_mfma_f32_16x16x32_bf16 v[86:89], v[162:165], v[200:203], v[86:89]
	v_mfma_f32_16x16x32_bf16 v[82:85], v[170:173], v[200:203], v[82:85]
	v_mfma_f32_16x16x32_bf16 v[70:73], v[162:165], v[208:211], v[70:73]
	v_mfma_f32_16x16x32_bf16 v[66:69], v[170:173], v[208:211], v[66:69]
	v_mfma_f32_16x16x32_bf16 v[118:121], v[166:169], v[188:191], v[118:121]
	v_mfma_f32_16x16x32_bf16 v[114:117], v[174:177], v[188:191], v[114:117]
	v_mfma_f32_16x16x32_bf16 v[102:105], v[166:169], v[196:199], v[102:105]
	v_mfma_f32_16x16x32_bf16 v[98:101], v[174:177], v[196:199], v[98:101]
	v_mfma_f32_16x16x32_bf16 v[86:89], v[166:169], v[204:207], v[86:89]
	v_mfma_f32_16x16x32_bf16 v[82:85], v[174:177], v[204:207], v[82:85]
	v_mfma_f32_16x16x32_bf16 v[70:73], v[166:169], v[212:215], v[70:73]
	v_mfma_f32_16x16x32_bf16 v[66:69], v[174:177], v[212:215], v[66:69]
	s_setprio 0
	s_barrier
	s_add_i32 s18, s20, s5
	v_lshl_add_u64 v[140:141], s[44:45], 0, v[0:1]
	s_mov_b32 m0, s18
	ds_read_b128 v[184:187], v145 offset:16384
	ds_read_b128 v[188:191], v145 offset:17408
	ds_read_b128 v[192:195], v145 offset:18432
	ds_read_b128 v[196:199], v145 offset:19456
	ds_read_b128 v[200:203], v145 offset:20480
	ds_read_b128 v[204:207], v145 offset:21504
	ds_read_b128 v[208:211], v145 offset:22528
	ds_read_b128 v[212:215], v145 offset:23552
	global_load_lds_dwordx4 v[140:141], off
	s_add_i32 m0, s18, 0x2000
	s_add_u32 s18, s44, 0x80000
	v_lshl_add_u64 v[216:217], s[44:45], 0, v[130:131]
	s_addc_u32 s19, s45, 0
	s_add_i32 s20, s24, s5
	global_load_lds_dwordx4 v[216:217], off
	v_lshl_add_u64 v[218:219], s[18:19], 0, v[0:1]
	s_mov_b32 m0, s20
	v_lshl_add_u64 v[220:221], s[46:47], 0, v[132:133]
	global_load_lds_dwordx4 v[218:219], off
	v_lshl_add_u64 v[218:219], s[18:19], 0, v[130:131]
	s_add_i32 m0, s20, 0x2000
	s_nop 0
	global_load_lds_dwordx4 v[218:219], off
	v_lshl_add_u64 v[218:219], s[46:47], 0, v[134:135]
	s_mov_b32 m0, s21
	s_nop 0
	global_load_lds_dwordx4 v[218:219], off
	s_mov_b32 m0, s22
	s_nop 0
	global_load_lds_dwordx4 v[220:221], off
	s_waitcnt vmcnt(8)
	s_waitcnt lgkmcnt(0)
	s_barrier
	s_setprio 1
	s_waitcnt lgkmcnt(0)
	v_mfma_f32_16x16x32_bf16 v[62:65], v[146:149], v[184:187], v[62:65]
	v_mfma_f32_16x16x32_bf16 v[58:61], v[154:157], v[184:187], v[58:61]
	v_mfma_f32_16x16x32_bf16 v[46:49], v[146:149], v[192:195], v[46:49]
	v_mfma_f32_16x16x32_bf16 v[42:45], v[154:157], v[192:195], v[42:45]
	v_mfma_f32_16x16x32_bf16 v[30:33], v[146:149], v[200:203], v[30:33]
	v_mfma_f32_16x16x32_bf16 v[26:29], v[154:157], v[200:203], v[26:29]
	v_mfma_f32_16x16x32_bf16 v[14:17], v[146:149], v[208:211], v[14:17]
	v_mfma_f32_16x16x32_bf16 v[10:13], v[154:157], v[208:211], v[10:13]
	v_mfma_f32_16x16x32_bf16 v[62:65], v[150:153], v[188:191], v[62:65]
	v_mfma_f32_16x16x32_bf16 v[58:61], v[158:161], v[188:191], v[58:61]
	v_mfma_f32_16x16x32_bf16 v[46:49], v[150:153], v[196:199], v[46:49]
	v_mfma_f32_16x16x32_bf16 v[42:45], v[158:161], v[196:199], v[42:45]
	v_mfma_f32_16x16x32_bf16 v[30:33], v[150:153], v[204:207], v[30:33]
	v_mfma_f32_16x16x32_bf16 v[26:29], v[158:161], v[204:207], v[26:29]
	v_mfma_f32_16x16x32_bf16 v[14:17], v[150:153], v[212:215], v[14:17]
	v_mfma_f32_16x16x32_bf16 v[10:13], v[158:161], v[212:215], v[10:13]
	s_setprio 0
	s_setprio 1
	v_mfma_f32_16x16x32_bf16 v[54:57], v[162:165], v[184:187], v[54:57]
	v_mfma_f32_16x16x32_bf16 v[50:53], v[170:173], v[184:187], v[50:53]
	v_mfma_f32_16x16x32_bf16 v[38:41], v[162:165], v[192:195], v[38:41]
	v_mfma_f32_16x16x32_bf16 v[34:37], v[170:173], v[192:195], v[34:37]
	v_mfma_f32_16x16x32_bf16 v[22:25], v[162:165], v[200:203], v[22:25]
	v_mfma_f32_16x16x32_bf16 v[18:21], v[170:173], v[200:203], v[18:21]
	v_mfma_f32_16x16x32_bf16 v[6:9], v[162:165], v[208:211], v[6:9]
	v_mfma_f32_16x16x32_bf16 v[2:5], v[170:173], v[208:211], v[2:5]
	v_mfma_f32_16x16x32_bf16 v[54:57], v[166:169], v[188:191], v[54:57]
	v_mfma_f32_16x16x32_bf16 v[50:53], v[174:177], v[188:191], v[50:53]
	v_mfma_f32_16x16x32_bf16 v[38:41], v[166:169], v[196:199], v[38:41]
	v_mfma_f32_16x16x32_bf16 v[34:37], v[174:177], v[196:199], v[34:37]
	v_mfma_f32_16x16x32_bf16 v[22:25], v[166:169], v[204:207], v[22:25]
	v_mfma_f32_16x16x32_bf16 v[18:21], v[174:177], v[204:207], v[18:21]
	v_mfma_f32_16x16x32_bf16 v[6:9], v[166:169], v[212:215], v[6:9]
	v_mfma_f32_16x16x32_bf16 v[2:5], v[174:177], v[212:215], v[2:5]
	s_setprio 0
	s_barrier
	s_add_i32 s20, 0, 0x18000
	s_add_i32 s24, 0, 0x1c000
	v_add_u32_e32 v158, s20, v144
	v_add_u32_e32 v174, s24, v144
	ds_read_b128 v[146:149], v158
	ds_read_b128 v[150:153], v158 offset:1024
	ds_read_b128 v[154:157], v158 offset:2048
	ds_read_b128 v[158:161], v158 offset:3072
	ds_read_b128 v[162:165], v174
	ds_read_b128 v[166:169], v174 offset:1024
	ds_read_b128 v[170:173], v174 offset:2048
	ds_read_b128 v[174:177], v174 offset:3072
	s_add_u32 s18, s46, 0x80000
	s_addc_u32 s19, s47, 0
	s_mov_b32 m0, s33
	v_lshl_add_u64 v[222:223], s[18:19], 0, v[134:135]
	ds_read_b128 v[184:187], v145 offset:32768
	ds_read_b128 v[188:191], v145 offset:33792
	ds_read_b128 v[192:195], v145 offset:34816
	ds_read_b128 v[196:199], v145 offset:35840
	ds_read_b128 v[200:203], v145 offset:36864
	ds_read_b128 v[204:207], v145 offset:37888
	ds_read_b128 v[208:211], v145 offset:38912
	ds_read_b128 v[212:215], v145 offset:39936
	global_load_lds_dwordx4 v[222:223], off
	v_lshl_add_u64 v[222:223], s[18:19], 0, v[132:133]
	s_mov_b32 m0, s36
	s_nop 0
	global_load_lds_dwordx4 v[222:223], off
	s_waitcnt vmcnt(8)
	s_waitcnt lgkmcnt(0)
	s_barrier
	s_setprio 1
	s_waitcnt lgkmcnt(0)
	v_mfma_f32_16x16x32_bf16 v[126:129], v[146:149], v[184:187], v[126:129]
	v_mfma_f32_16x16x32_bf16 v[122:125], v[154:157], v[184:187], v[122:125]
	v_mfma_f32_16x16x32_bf16 v[110:113], v[146:149], v[192:195], v[110:113]
	v_mfma_f32_16x16x32_bf16 v[106:109], v[154:157], v[192:195], v[106:109]
	v_mfma_f32_16x16x32_bf16 v[94:97], v[146:149], v[200:203], v[94:97]
	v_mfma_f32_16x16x32_bf16 v[90:93], v[154:157], v[200:203], v[90:93]
	v_mfma_f32_16x16x32_bf16 v[78:81], v[146:149], v[208:211], v[78:81]
	v_mfma_f32_16x16x32_bf16 v[74:77], v[154:157], v[208:211], v[74:77]
	v_mfma_f32_16x16x32_bf16 v[126:129], v[150:153], v[188:191], v[126:129]
	v_mfma_f32_16x16x32_bf16 v[122:125], v[158:161], v[188:191], v[122:125]
	v_mfma_f32_16x16x32_bf16 v[110:113], v[150:153], v[196:199], v[110:113]
	v_mfma_f32_16x16x32_bf16 v[106:109], v[158:161], v[196:199], v[106:109]
	v_mfma_f32_16x16x32_bf16 v[94:97], v[150:153], v[204:207], v[94:97]
	v_mfma_f32_16x16x32_bf16 v[90:93], v[158:161], v[204:207], v[90:93]
	v_mfma_f32_16x16x32_bf16 v[78:81], v[150:153], v[212:215], v[78:81]
	v_mfma_f32_16x16x32_bf16 v[74:77], v[158:161], v[212:215], v[74:77]
	s_setprio 0
	s_setprio 1
	v_mfma_f32_16x16x32_bf16 v[118:121], v[162:165], v[184:187], v[118:121]
	v_mfma_f32_16x16x32_bf16 v[114:117], v[170:173], v[184:187], v[114:117]
	v_mfma_f32_16x16x32_bf16 v[102:105], v[162:165], v[192:195], v[102:105]
	v_mfma_f32_16x16x32_bf16 v[98:101], v[170:173], v[192:195], v[98:101]
	v_mfma_f32_16x16x32_bf16 v[86:89], v[162:165], v[200:203], v[86:89]
	v_mfma_f32_16x16x32_bf16 v[82:85], v[170:173], v[200:203], v[82:85]
	v_mfma_f32_16x16x32_bf16 v[70:73], v[162:165], v[208:211], v[70:73]
	v_mfma_f32_16x16x32_bf16 v[66:69], v[170:173], v[208:211], v[66:69]
	v_mfma_f32_16x16x32_bf16 v[118:121], v[166:169], v[188:191], v[118:121]
	v_mfma_f32_16x16x32_bf16 v[114:117], v[174:177], v[188:191], v[114:117]
	v_mfma_f32_16x16x32_bf16 v[102:105], v[166:169], v[196:199], v[102:105]
	v_mfma_f32_16x16x32_bf16 v[98:101], v[174:177], v[196:199], v[98:101]
	v_mfma_f32_16x16x32_bf16 v[86:89], v[166:169], v[204:207], v[86:89]
	v_mfma_f32_16x16x32_bf16 v[82:85], v[174:177], v[204:207], v[82:85]
	v_mfma_f32_16x16x32_bf16 v[70:73], v[166:169], v[212:215], v[70:73]
	v_mfma_f32_16x16x32_bf16 v[66:69], v[174:177], v[212:215], v[66:69]
	s_setprio 0
	s_barrier
	s_add_i32 s18, s20, s5
	v_lshl_add_u64 v[140:141], v[140:141], 0, s[90:91]
	s_mov_b32 m0, s18
	ds_read_b128 v[184:187], v145 offset:49152
	ds_read_b128 v[188:191], v145 offset:50176
	ds_read_b128 v[192:195], v145 offset:51200
	ds_read_b128 v[196:199], v145 offset:52224
	ds_read_b128 v[200:203], v145 offset:53248
	ds_read_b128 v[204:207], v145 offset:54272
	ds_read_b128 v[208:211], v145 offset:55296
	ds_read_b128 v[212:215], v145 offset:56320
	global_load_lds_dwordx4 v[140:141], off
	s_add_i32 m0, s18, 0x2000
	s_add_u32 s18, s44, 0x80080
	v_lshl_add_u64 v[140:141], v[216:217], 0, s[90:91]
	s_addc_u32 s19, s45, 0
	s_add_i32 s20, s24, s5
	global_load_lds_dwordx4 v[140:141], off
	v_lshl_add_u64 v[140:141], s[18:19], 0, v[0:1]
	s_mov_b32 m0, s20
	s_nop 0
	global_load_lds_dwordx4 v[140:141], off
	v_lshl_add_u64 v[140:141], s[18:19], 0, v[130:131]
	s_add_i32 m0, s20, 0x2000
	s_nop 0
	global_load_lds_dwordx4 v[140:141], off
	v_lshl_add_u64 v[140:141], v[218:219], 0, s[90:91]
	s_mov_b32 m0, s48
	s_nop 0
	global_load_lds_dwordx4 v[140:141], off
	v_lshl_add_u64 v[140:141], v[220:221], 0, s[90:91]
	s_mov_b32 m0, s49
	s_nop 0
	global_load_lds_dwordx4 v[140:141], off
	s_waitcnt vmcnt(8)
	s_waitcnt lgkmcnt(0)
	s_barrier
	s_setprio 1
	s_waitcnt lgkmcnt(0)
	v_mfma_f32_16x16x32_bf16 v[62:65], v[146:149], v[184:187], v[62:65]
	v_mfma_f32_16x16x32_bf16 v[58:61], v[154:157], v[184:187], v[58:61]
	v_mfma_f32_16x16x32_bf16 v[46:49], v[146:149], v[192:195], v[46:49]
	v_mfma_f32_16x16x32_bf16 v[42:45], v[154:157], v[192:195], v[42:45]
	v_mfma_f32_16x16x32_bf16 v[30:33], v[146:149], v[200:203], v[30:33]
	v_mfma_f32_16x16x32_bf16 v[26:29], v[154:157], v[200:203], v[26:29]
	v_mfma_f32_16x16x32_bf16 v[14:17], v[146:149], v[208:211], v[14:17]
	v_mfma_f32_16x16x32_bf16 v[10:13], v[154:157], v[208:211], v[10:13]
	v_mfma_f32_16x16x32_bf16 v[62:65], v[150:153], v[188:191], v[62:65]
	v_mfma_f32_16x16x32_bf16 v[58:61], v[158:161], v[188:191], v[58:61]
	v_mfma_f32_16x16x32_bf16 v[46:49], v[150:153], v[196:199], v[46:49]
	v_mfma_f32_16x16x32_bf16 v[42:45], v[158:161], v[196:199], v[42:45]
	v_mfma_f32_16x16x32_bf16 v[30:33], v[150:153], v[204:207], v[30:33]
	v_mfma_f32_16x16x32_bf16 v[26:29], v[158:161], v[204:207], v[26:29]
	v_mfma_f32_16x16x32_bf16 v[14:17], v[150:153], v[212:215], v[14:17]
	v_mfma_f32_16x16x32_bf16 v[10:13], v[158:161], v[212:215], v[10:13]
	s_setprio 0
	s_setprio 1
	v_mfma_f32_16x16x32_bf16 v[54:57], v[162:165], v[184:187], v[54:57]
	v_mfma_f32_16x16x32_bf16 v[50:53], v[170:173], v[184:187], v[50:53]
	v_mfma_f32_16x16x32_bf16 v[38:41], v[162:165], v[192:195], v[38:41]
	v_mfma_f32_16x16x32_bf16 v[34:37], v[170:173], v[192:195], v[34:37]
	v_mfma_f32_16x16x32_bf16 v[22:25], v[162:165], v[200:203], v[22:25]
	v_mfma_f32_16x16x32_bf16 v[18:21], v[170:173], v[200:203], v[18:21]
	v_mfma_f32_16x16x32_bf16 v[6:9], v[162:165], v[208:211], v[6:9]
	v_mfma_f32_16x16x32_bf16 v[2:5], v[170:173], v[208:211], v[2:5]
	v_mfma_f32_16x16x32_bf16 v[54:57], v[166:169], v[188:191], v[54:57]
	v_mfma_f32_16x16x32_bf16 v[50:53], v[174:177], v[188:191], v[50:53]
	v_mfma_f32_16x16x32_bf16 v[38:41], v[166:169], v[196:199], v[38:41]
	v_mfma_f32_16x16x32_bf16 v[34:37], v[174:177], v[196:199], v[34:37]
	v_mfma_f32_16x16x32_bf16 v[22:25], v[166:169], v[204:207], v[22:25]
	v_mfma_f32_16x16x32_bf16 v[18:21], v[174:177], v[204:207], v[18:21]
	v_mfma_f32_16x16x32_bf16 v[6:9], v[166:169], v[212:215], v[6:9]
	v_mfma_f32_16x16x32_bf16 v[2:5], v[174:177], v[212:215], v[2:5]
	s_setprio 0
	s_add_i32 s59, s59, 2
	s_add_u32 s42, s42, 0x100
	s_addc_u32 s43, s43, 0
	s_add_u32 s17, s17, 0x100
	s_addc_u32 s58, s58, 0
	s_cmp_gt_u32 s59, 29
	s_barrier
	s_cbranch_scc0 .LBB0_1003
	s_and_b64 vcc, exec, s[8:9]
	s_cbranch_vccz .LBB0_1006
	s_barrier

.LBB0_1081:
	s_cmp_eq_u32 s81, s42
	s_cselect_b64 s[18:19], -1, 0
	s_add_i32 s93, s93, 2
	s_add_u32 s20, s38, s42
	s_addc_u32 s24, s39, s43
	s_add_u32 s20, s20, 0x100
	s_addc_u32 s24, s24, 0
	s_and_b64 s[44:45], s[18:19], exec
	s_cselect_b32 s47, s67, s24
	s_cselect_b32 s46, s74, s20
	s_and_b64 s[44:45], s[40:41], s[18:19]
	s_and_b64 s[44:45], s[44:45], exec
	s_cselect_b32 s20, 0, s37
	s_cselect_b32 s24, 0x200000, s36
	s_add_i32 s25, 0, 0x10000
	s_add_u32 s44, s89, s42
	s_addc_u32 s45, s92, s43
	s_and_b64 s[18:19], s[18:19], exec
	s_cselect_b32 s45, s75, s45
	s_cselect_b32 s44, s79, s44
	s_add_i32 s69, 0, 0x14000
	v_add_u32_e32 v146, s25, v204
	v_add_u32_e32 v162, s69, v204
	ds_read_b128 v[118:121], v146
	ds_read_b128 v[122:125], v146 offset:1024
	ds_read_b128 v[126:129], v146 offset:2048
	ds_read_b128 v[146:149], v146 offset:3072
	ds_read_b128 v[150:153], v162
	ds_read_b128 v[154:157], v162 offset:1024
	ds_read_b128 v[158:161], v162 offset:2048
	ds_read_b128 v[162:165], v162 offset:3072
	v_lshl_add_u64 v[218:219], v[114:115], 0, s[42:43]
	s_add_i32 m0, s48, 0xc000
	ds_read_b128 v[166:169], v205
	ds_read_b128 v[170:173], v205 offset:1024
	ds_read_b128 v[174:177], v205 offset:2048
	ds_read_b128 v[194:197], v205 offset:3072
	ds_read_b128 v[198:201], v205 offset:4096
	ds_read_b128 v[206:209], v205 offset:5120
	ds_read_b128 v[210:213], v205 offset:6144
	ds_read_b128 v[214:217], v205 offset:7168
	global_load_lds_dwordx4 v[218:219], off
	v_lshl_add_u64 v[218:219], v[116:117], 0, s[42:43]
	s_add_i32 m0, s48, 0xe000
	s_nop 0
	global_load_lds_dwordx4 v[218:219], off
	s_waitcnt vmcnt(8)
	s_waitcnt lgkmcnt(0)
	s_barrier
	s_setprio 1
	s_waitcnt lgkmcnt(0)
	v_mfma_f32_16x16x32_bf16 v[142:145], v[118:121], v[166:169], v[142:145]
	v_mfma_f32_16x16x32_bf16 v[138:141], v[126:129], v[166:169], v[138:141]
	v_mfma_f32_16x16x32_bf16 v[110:113], v[118:121], v[174:177], v[110:113]
	v_mfma_f32_16x16x32_bf16 v[106:109], v[126:129], v[174:177], v[106:109]
	v_mfma_f32_16x16x32_bf16 v[94:97], v[118:121], v[198:201], v[94:97]
	v_mfma_f32_16x16x32_bf16 v[90:93], v[126:129], v[198:201], v[90:93]
	v_mfma_f32_16x16x32_bf16 v[78:81], v[118:121], v[210:213], v[78:81]
	v_mfma_f32_16x16x32_bf16 v[74:77], v[126:129], v[210:213], v[74:77]
	v_mfma_f32_16x16x32_bf16 v[142:145], v[122:125], v[170:173], v[142:145]
	v_mfma_f32_16x16x32_bf16 v[138:141], v[146:149], v[170:173], v[138:141]
	v_mfma_f32_16x16x32_bf16 v[110:113], v[122:125], v[194:197], v[110:113]
	v_mfma_f32_16x16x32_bf16 v[106:109], v[146:149], v[194:197], v[106:109]
	v_mfma_f32_16x16x32_bf16 v[94:97], v[122:125], v[206:209], v[94:97]
	v_mfma_f32_16x16x32_bf16 v[90:93], v[146:149], v[206:209], v[90:93]
	v_mfma_f32_16x16x32_bf16 v[78:81], v[122:125], v[214:217], v[78:81]
	v_mfma_f32_16x16x32_bf16 v[74:77], v[146:149], v[214:217], v[74:77]
	s_setprio 0
	s_setprio 1
	v_mfma_f32_16x16x32_bf16 v[134:137], v[150:153], v[166:169], v[134:137]
	v_mfma_f32_16x16x32_bf16 v[130:133], v[158:161], v[166:169], v[130:133]
	v_mfma_f32_16x16x32_bf16 v[102:105], v[150:153], v[174:177], v[102:105]
	v_mfma_f32_16x16x32_bf16 v[98:101], v[158:161], v[174:177], v[98:101]
	v_mfma_f32_16x16x32_bf16 v[86:89], v[150:153], v[198:201], v[86:89]
	v_mfma_f32_16x16x32_bf16 v[82:85], v[158:161], v[198:201], v[82:85]
	v_mfma_f32_16x16x32_bf16 v[70:73], v[150:153], v[210:213], v[70:73]
	v_mfma_f32_16x16x32_bf16 v[66:69], v[158:161], v[210:213], v[66:69]
	v_mfma_f32_16x16x32_bf16 v[134:137], v[154:157], v[170:173], v[134:137]
	v_mfma_f32_16x16x32_bf16 v[130:133], v[162:165], v[170:173], v[130:133]
	v_mfma_f32_16x16x32_bf16 v[102:105], v[154:157], v[194:197], v[102:105]
	v_mfma_f32_16x16x32_bf16 v[98:101], v[162:165], v[194:197], v[98:101]
	v_mfma_f32_16x16x32_bf16 v[86:89], v[154:157], v[206:209], v[86:89]
	v_mfma_f32_16x16x32_bf16 v[82:85], v[162:165], v[206:209], v[82:85]
	v_mfma_f32_16x16x32_bf16 v[70:73], v[154:157], v[214:217], v[70:73]
	v_mfma_f32_16x16x32_bf16 v[66:69], v[162:165], v[214:217], v[66:69]
	s_setprio 0
	s_barrier
	s_add_i32 s18, s25, s33
	v_lshl_add_u64 v[218:219], s[44:45], 0, v[0:1]
	s_mov_b32 m0, s18
	ds_read_b128 v[166:169], v205 offset:16384
	ds_read_b128 v[170:173], v205 offset:17408
	ds_read_b128 v[174:177], v205 offset:18432
	ds_read_b128 v[194:197], v205 offset:19456
	ds_read_b128 v[198:201], v205 offset:20480
	ds_read_b128 v[206:209], v205 offset:21504
	ds_read_b128 v[210:213], v205 offset:22528
	ds_read_b128 v[214:217], v205 offset:23552
	global_load_lds_dwordx4 v[218:219], off
	s_add_i32 m0, s18, 0x2000
	s_add_u32 s18, s44, 0x200000
	v_lshl_add_u64 v[220:221], s[44:45], 0, v[188:189]
	s_addc_u32 s19, s45, 0
	s_add_i32 s25, s69, s33
	global_load_lds_dwordx4 v[220:221], off
	v_lshl_add_u64 v[222:223], s[18:19], 0, v[0:1]
	s_mov_b32 m0, s25
	v_lshl_add_u64 v[224:225], s[46:47], 0, v[186:187]
	global_load_lds_dwordx4 v[222:223], off
	v_lshl_add_u64 v[222:223], s[18:19], 0, v[188:189]
	s_add_i32 m0, s25, 0x2000
	s_nop 0
	global_load_lds_dwordx4 v[222:223], off
	v_lshl_add_u64 v[222:223], s[46:47], 0, v[184:185]
	s_mov_b32 m0, s48
	s_nop 0
	global_load_lds_dwordx4 v[222:223], off
	s_mov_b32 m0, s49
	s_nop 0
	global_load_lds_dwordx4 v[224:225], off
	s_waitcnt vmcnt(8)
	s_waitcnt lgkmcnt(0)
	s_barrier
	s_setprio 1
	s_waitcnt lgkmcnt(0)
	v_mfma_f32_16x16x32_bf16 v[62:65], v[118:121], v[166:169], v[62:65]
	v_mfma_f32_16x16x32_bf16 v[58:61], v[126:129], v[166:169], v[58:61]
	v_mfma_f32_16x16x32_bf16 v[46:49], v[118:121], v[174:177], v[46:49]
	v_mfma_f32_16x16x32_bf16 v[42:45], v[126:129], v[174:177], v[42:45]
	v_mfma_f32_16x16x32_bf16 v[30:33], v[118:121], v[198:201], v[30:33]
	v_mfma_f32_16x16x32_bf16 v[26:29], v[126:129], v[198:201], v[26:29]
	v_mfma_f32_16x16x32_bf16 v[14:17], v[118:121], v[210:213], v[14:17]
	v_mfma_f32_16x16x32_bf16 v[10:13], v[126:129], v[210:213], v[10:13]
	v_mfma_f32_16x16x32_bf16 v[62:65], v[122:125], v[170:173], v[62:65]
	v_mfma_f32_16x16x32_bf16 v[58:61], v[146:149], v[170:173], v[58:61]
	v_mfma_f32_16x16x32_bf16 v[46:49], v[122:125], v[194:197], v[46:49]
	v_mfma_f32_16x16x32_bf16 v[42:45], v[146:149], v[194:197], v[42:45]
	v_mfma_f32_16x16x32_bf16 v[30:33], v[122:125], v[206:209], v[30:33]
	v_mfma_f32_16x16x32_bf16 v[26:29], v[146:149], v[206:209], v[26:29]
	v_mfma_f32_16x16x32_bf16 v[14:17], v[122:125], v[214:217], v[14:17]
	v_mfma_f32_16x16x32_bf16 v[10:13], v[146:149], v[214:217], v[10:13]
	s_setprio 0
	s_setprio 1
	v_mfma_f32_16x16x32_bf16 v[54:57], v[150:153], v[166:169], v[54:57]
	v_mfma_f32_16x16x32_bf16 v[50:53], v[158:161], v[166:169], v[50:53]
	v_mfma_f32_16x16x32_bf16 v[38:41], v[150:153], v[174:177], v[38:41]
	v_mfma_f32_16x16x32_bf16 v[34:37], v[158:161], v[174:177], v[34:37]
	v_mfma_f32_16x16x32_bf16 v[22:25], v[150:153], v[198:201], v[22:25]
	v_mfma_f32_16x16x32_bf16 v[18:21], v[158:161], v[198:201], v[18:21]
	v_mfma_f32_16x16x32_bf16 v[6:9], v[150:153], v[210:213], v[6:9]
	v_mfma_f32_16x16x32_bf16 v[2:5], v[158:161], v[210:213], v[2:5]
	v_mfma_f32_16x16x32_bf16 v[54:57], v[154:157], v[170:173], v[54:57]
	v_mfma_f32_16x16x32_bf16 v[50:53], v[162:165], v[170:173], v[50:53]
	v_mfma_f32_16x16x32_bf16 v[38:41], v[154:157], v[194:197], v[38:41]
	v_mfma_f32_16x16x32_bf16 v[34:37], v[162:165], v[194:197], v[34:37]
	v_mfma_f32_16x16x32_bf16 v[22:25], v[154:157], v[206:209], v[22:25]
	v_mfma_f32_16x16x32_bf16 v[18:21], v[162:165], v[206:209], v[18:21]
	v_mfma_f32_16x16x32_bf16 v[6:9], v[154:157], v[214:217], v[6:9]
	v_mfma_f32_16x16x32_bf16 v[2:5], v[162:165], v[214:217], v[2:5]
	s_setprio 0
	s_barrier
	s_add_i32 s25, 0, 0x18000
	s_add_i32 s69, 0, 0x1c000
	v_add_u32_e32 v146, s25, v204
	v_add_u32_e32 v162, s69, v204
	ds_read_b128 v[118:121], v146
	ds_read_b128 v[122:125], v146 offset:1024
	ds_read_b128 v[126:129], v146 offset:2048
	ds_read_b128 v[146:149], v146 offset:3072
	ds_read_b128 v[150:153], v162
	ds_read_b128 v[154:157], v162 offset:1024
	ds_read_b128 v[158:161], v162 offset:2048
	ds_read_b128 v[162:165], v162 offset:3072
	s_add_u32 s18, s46, s24
	s_addc_u32 s19, s47, s20
	s_mov_b32 m0, s52
	v_lshl_add_u64 v[226:227], s[18:19], 0, v[184:185]
	ds_read_b128 v[166:169], v205 offset:32768
	ds_read_b128 v[170:173], v205 offset:33792
	ds_read_b128 v[174:177], v205 offset:34816
	ds_read_b128 v[194:197], v205 offset:35840
	ds_read_b128 v[198:201], v205 offset:36864
	ds_read_b128 v[206:209], v205 offset:37888
	ds_read_b128 v[210:213], v205 offset:38912
	ds_read_b128 v[214:217], v205 offset:39936
	global_load_lds_dwordx4 v[226:227], off
	v_lshl_add_u64 v[226:227], s[18:19], 0, v[186:187]
	s_mov_b32 m0, s53
	s_nop 0
	global_load_lds_dwordx4 v[226:227], off
	s_waitcnt vmcnt(8)
	s_waitcnt lgkmcnt(0)
	s_barrier
	s_setprio 1
	s_waitcnt lgkmcnt(0)
	v_mfma_f32_16x16x32_bf16 v[142:145], v[118:121], v[166:169], v[142:145]
	v_mfma_f32_16x16x32_bf16 v[138:141], v[126:129], v[166:169], v[138:141]
	v_mfma_f32_16x16x32_bf16 v[110:113], v[118:121], v[174:177], v[110:113]
	v_mfma_f32_16x16x32_bf16 v[106:109], v[126:129], v[174:177], v[106:109]
	v_mfma_f32_16x16x32_bf16 v[94:97], v[118:121], v[198:201], v[94:97]
	v_mfma_f32_16x16x32_bf16 v[90:93], v[126:129], v[198:201], v[90:93]
	v_mfma_f32_16x16x32_bf16 v[78:81], v[118:121], v[210:213], v[78:81]
	v_mfma_f32_16x16x32_bf16 v[74:77], v[126:129], v[210:213], v[74:77]
	v_mfma_f32_16x16x32_bf16 v[142:145], v[122:125], v[170:173], v[142:145]
	v_mfma_f32_16x16x32_bf16 v[138:141], v[146:149], v[170:173], v[138:141]
	v_mfma_f32_16x16x32_bf16 v[110:113], v[122:125], v[194:197], v[110:113]
	v_mfma_f32_16x16x32_bf16 v[106:109], v[146:149], v[194:197], v[106:109]
	v_mfma_f32_16x16x32_bf16 v[94:97], v[122:125], v[206:209], v[94:97]
	v_mfma_f32_16x16x32_bf16 v[90:93], v[146:149], v[206:209], v[90:93]
	v_mfma_f32_16x16x32_bf16 v[78:81], v[122:125], v[214:217], v[78:81]
	v_mfma_f32_16x16x32_bf16 v[74:77], v[146:149], v[214:217], v[74:77]
	s_setprio 0
	s_setprio 1
	v_mfma_f32_16x16x32_bf16 v[134:137], v[150:153], v[166:169], v[134:137]
	v_mfma_f32_16x16x32_bf16 v[130:133], v[158:161], v[166:169], v[130:133]
	v_mfma_f32_16x16x32_bf16 v[102:105], v[150:153], v[174:177], v[102:105]
	v_mfma_f32_16x16x32_bf16 v[98:101], v[158:161], v[174:177], v[98:101]
	v_mfma_f32_16x16x32_bf16 v[86:89], v[150:153], v[198:201], v[86:89]
	v_mfma_f32_16x16x32_bf16 v[82:85], v[158:161], v[198:201], v[82:85]
	v_mfma_f32_16x16x32_bf16 v[70:73], v[150:153], v[210:213], v[70:73]
	v_mfma_f32_16x16x32_bf16 v[66:69], v[158:161], v[210:213], v[66:69]
	v_mfma_f32_16x16x32_bf16 v[134:137], v[154:157], v[170:173], v[134:137]
	v_mfma_f32_16x16x32_bf16 v[130:133], v[162:165], v[170:173], v[130:133]
	v_mfma_f32_16x16x32_bf16 v[102:105], v[154:157], v[194:197], v[102:105]
	v_mfma_f32_16x16x32_bf16 v[98:101], v[162:165], v[194:197], v[98:101]
	v_mfma_f32_16x16x32_bf16 v[86:89], v[154:157], v[206:209], v[86:89]
	v_mfma_f32_16x16x32_bf16 v[82:85], v[162:165], v[206:209], v[82:85]
	v_mfma_f32_16x16x32_bf16 v[70:73], v[154:157], v[214:217], v[70:73]
	v_mfma_f32_16x16x32_bf16 v[66:69], v[162:165], v[214:217], v[66:69]
	s_setprio 0
	s_barrier
	s_add_i32 s18, s25, s33
	v_lshl_add_u64 v[218:219], v[218:219], 0, s[90:91]
	s_mov_b32 m0, s18
	ds_read_b128 v[166:169], v205 offset:49152
	ds_read_b128 v[170:173], v205 offset:50176
	ds_read_b128 v[174:177], v205 offset:51200
	ds_read_b128 v[194:197], v205 offset:52224
	ds_read_b128 v[198:201], v205 offset:53248
	ds_read_b128 v[206:209], v205 offset:54272
	ds_read_b128 v[210:213], v205 offset:55296
	ds_read_b128 v[214:217], v205 offset:56320
	global_load_lds_dwordx4 v[218:219], off
	s_add_i32 m0, s18, 0x2000
	s_add_u32 s18, s44, 0x200080
	v_lshl_add_u64 v[218:219], v[220:221], 0, s[90:91]
	s_addc_u32 s19, s45, 0
	s_add_i32 s20, s69, s33
	global_load_lds_dwordx4 v[218:219], off
	v_lshl_add_u64 v[218:219], s[18:19], 0, v[0:1]
	s_mov_b32 m0, s20
	s_nop 0
	global_load_lds_dwordx4 v[218:219], off
	v_lshl_add_u64 v[218:219], s[18:19], 0, v[188:189]
	s_add_i32 m0, s20, 0x2000
	s_nop 0
	global_load_lds_dwordx4 v[218:219], off
	v_lshl_add_u64 v[218:219], v[222:223], 0, s[90:91]
	s_mov_b32 m0, s58
	s_nop 0
	global_load_lds_dwordx4 v[218:219], off
	v_lshl_add_u64 v[218:219], v[224:225], 0, s[90:91]
	s_mov_b32 m0, s59
	s_nop 0
	global_load_lds_dwordx4 v[218:219], off
	s_waitcnt vmcnt(8)
	s_waitcnt lgkmcnt(0)
	s_barrier
	s_setprio 1
	s_waitcnt lgkmcnt(0)
	v_mfma_f32_16x16x32_bf16 v[62:65], v[118:121], v[166:169], v[62:65]
	v_mfma_f32_16x16x32_bf16 v[58:61], v[126:129], v[166:169], v[58:61]
	v_mfma_f32_16x16x32_bf16 v[46:49], v[118:121], v[174:177], v[46:49]
	v_mfma_f32_16x16x32_bf16 v[42:45], v[126:129], v[174:177], v[42:45]
	v_mfma_f32_16x16x32_bf16 v[30:33], v[118:121], v[198:201], v[30:33]
	v_mfma_f32_16x16x32_bf16 v[26:29], v[126:129], v[198:201], v[26:29]
	v_mfma_f32_16x16x32_bf16 v[14:17], v[118:121], v[210:213], v[14:17]
	v_mfma_f32_16x16x32_bf16 v[10:13], v[126:129], v[210:213], v[10:13]
	v_mfma_f32_16x16x32_bf16 v[62:65], v[122:125], v[170:173], v[62:65]
	v_mfma_f32_16x16x32_bf16 v[58:61], v[146:149], v[170:173], v[58:61]
	v_mfma_f32_16x16x32_bf16 v[46:49], v[122:125], v[194:197], v[46:49]
	v_mfma_f32_16x16x32_bf16 v[42:45], v[146:149], v[194:197], v[42:45]
	v_mfma_f32_16x16x32_bf16 v[30:33], v[122:125], v[206:209], v[30:33]
	v_mfma_f32_16x16x32_bf16 v[26:29], v[146:149], v[206:209], v[26:29]
	v_mfma_f32_16x16x32_bf16 v[14:17], v[122:125], v[214:217], v[14:17]
	v_mfma_f32_16x16x32_bf16 v[10:13], v[146:149], v[214:217], v[10:13]
	s_setprio 0
	s_setprio 1
	v_mfma_f32_16x16x32_bf16 v[54:57], v[150:153], v[166:169], v[54:57]
	v_mfma_f32_16x16x32_bf16 v[50:53], v[158:161], v[166:169], v[50:53]
	v_mfma_f32_16x16x32_bf16 v[38:41], v[150:153], v[174:177], v[38:41]
	v_mfma_f32_16x16x32_bf16 v[34:37], v[158:161], v[174:177], v[34:37]
	v_mfma_f32_16x16x32_bf16 v[22:25], v[150:153], v[198:201], v[22:25]
	v_mfma_f32_16x16x32_bf16 v[18:21], v[158:161], v[198:201], v[18:21]
	v_mfma_f32_16x16x32_bf16 v[6:9], v[150:153], v[210:213], v[6:9]
	v_mfma_f32_16x16x32_bf16 v[2:5], v[158:161], v[210:213], v[2:5]
	v_mfma_f32_16x16x32_bf16 v[54:57], v[154:157], v[170:173], v[54:57]
	v_mfma_f32_16x16x32_bf16 v[50:53], v[162:165], v[170:173], v[50:53]
	v_mfma_f32_16x16x32_bf16 v[38:41], v[154:157], v[194:197], v[38:41]
	v_mfma_f32_16x16x32_bf16 v[34:37], v[162:165], v[194:197], v[34:37]
	v_mfma_f32_16x16x32_bf16 v[22:25], v[154:157], v[206:209], v[22:25]
	v_mfma_f32_16x16x32_bf16 v[18:21], v[162:165], v[206:209], v[18:21]
	v_mfma_f32_16x16x32_bf16 v[6:9], v[154:157], v[214:217], v[6:9]
	v_mfma_f32_16x16x32_bf16 v[2:5], v[162:165], v[214:217], v[2:5]
	s_setprio 0
	s_add_u32 s42, s42, 0x100
	s_addc_u32 s43, s43, 0
	s_cmp_ge_u32 s93, s54
	s_barrier
	s_cbranch_scc0 .LBB0_1081
	s_and_b64 vcc, exec, s[10:11]
	s_cbranch_vccz .LBB0_1084
	s_barrier
